# adds: s_setprio toggles around the K-loop MFMA blocks removed (96)
# speedup vs baseline: 1.0037x; 1.0037x over previous
;     __host__ __device__ __forceinline__ bool next(int i, Unit& u) const { const int vv = vid + (i / 5) * G; if (vv >= 256) return false; u.pm = vv >> 2; u.pn = (vv & 3) + 4 * (i % 5); return true; }
; #define PG8_STAGE(bufoff, gbase, voff) do { _Pragma("unroll") for (int _i = 0; _i < 2; ++_i) \
;         __builtin_amdgcn_global_load_lds((const unsigned*)((const char*)(gbase) + (voff)[_i]), (PG8_LAS unsigned*)(lds + (bufoff) + ldsw + _i * 8192), 16, 0, 0); } while (0)
; #define PG8_LDA(dst, b, h) do { _Pragma("unroll") for (int m = 0; m < 4; ++m) _Pragma("unroll") for (int k = 0; k < 2; ++k) dst[m][k] = *(const PG8_LAS bf16x8*)(lds + PG8_SA(b, h) + aoff + m * 2048 + k * 1024); } while (0)
; #define PG8_LDB(dst, b, h) do { _Pragma("unroll") for (int n = 0; n < 2; ++n) _Pragma("unroll") for (int k = 0; k < 2; ++k) dst[n][k] = *(const PG8_LAS bf16x8*)(lds + PG8_SB(b, h) + boff + n * 2048 + k * 1024); } while (0)
; #define PG8_WAIT_V(n) asm volatile("s_waitcnt vmcnt(" #n ")" ::: "memory")
; #define PG8_WAIT_L(n) asm volatile("s_waitcnt lgkmcnt(" #n ")" ::: "memory")
; #define PG8_BAR __builtin_amdgcn_s_barrier()
; #define PG8_SCHED __builtin_amdgcn_sched_barrier(0)
;     ...
;         const bool has_next = S.next(ui + 1, nxt);
;         const char* nA = has_next ? (const char*)g.A + (size_t)nxt.pm * tstepA + (size_t)nxt.pn * APN + kofA : cA; const char* nB = has_next ? (const char*)g.Bt + (size_t)nxt.pn * tstepB + S.b_off(nxt) + kofB : cB;
;         for (int t = 0; t < nt; t += 2) {
;             const bool last = (t == nt - 2);
;             const char* a1 = cA + (ptrdiff_t)(t + 1) * kstepA;
;             const char* a2 = last ? nA : cA + (ptrdiff_t)(t + 2) * kstepA; const char* b2 = last ? nB : cB + (ptrdiff_t)(t + 2) * kstep;
;             const char* a3 = a2 + kstepA; const char* b3 = b2 + kstep;
;             if (last && has_next) S.a_ready(nxt);
;             if constexpr (SP2) {
;             PG8_LDB(B0, 0, 0); PG8_LDB(B1, 0, 1); PG8_SCHED; PG8_LDA(At, 0, 0); PG8_STAGE(PG8_SA(1, 1), a1 + hstepA, voffA);
;             PG8_WAIT_V(8); PG8_WAIT_L(0); PG8_BAR; PG8_MMA(0, 0, At, B0); PG8_MMA(0, 1, At, B1); PG8_BAR; PG8_SCHED;
;             PG8_LDA(At, 0, 1); PG8_STAGE(PG8_SB(0, 0), b2, voffB); PG8_STAGE(PG8_SB(0, 1), b2 + hstepB, voffB); PG8_STAGE(PG8_SA(0, 0), a2, voffA);
.LBB0_97:
	s_mov_b64 s[30:31], s[6:7]
	s_ashr_i32 s6, s14, 2
	s_and_b32 s6, s6, -8
	s_and_b32 s7, s14, 7
	s_mov_b32 s20, s58
	s_mov_b32 s21, s57
	v_cmp_lt_i64_e64 s[4:5], s[14:15], v[138:139]
	s_bfe_u32 s57, s14, 0x20003
	s_or_b32 s58, s6, s7
	s_and_b64 s[6:7], s[4:5], exec
	s_cselect_b32 s24, s58, s20
	s_cselect_b32 s6, s57, s21
	s_ashr_i32 s25, s24, 31
	s_lshl_b64 s[20:21], s[24:25], 20
	s_add_u32 s20, s2, s20
	s_addc_u32 s21, s3, s21
	s_ashr_i32 s7, s6, 31
	s_lshl_b64 s[6:7], s[6:7], 17
	s_add_u32 s20, s20, s6
	s_addc_u32 s21, s21, s7
	s_and_b64 s[28:29], s[4:5], exec
	ds_read_b128 v[0:3], v141
	ds_read_b128 v[4:7], v141 offset:1024
	ds_read_b128 v[8:11], v141 offset:2048
	ds_read_b128 v[12:15], v141 offset:3072
	ds_read_b128 v[16:19], v142
	ds_read_b128 v[20:23], v142 offset:1024
	ds_read_b128 v[24:27], v142 offset:2048
	ds_read_b128 v[28:31], v142 offset:3072
	s_cselect_b32 s29, s21, s27
	s_cselect_b32 s28, s20, s26
	s_add_u32 s25, s33, s6
	s_addc_u32 s34, s36, s7
	s_ashr_i32 s6, s24, 3
	s_ashr_i32 s7, s6, 31
	s_lshl_b64 s[6:7], s[6:7], 19
	s_add_u32 s6, s25, s6
	s_addc_u32 s7, s34, s7
	s_and_b64 s[24:25], s[4:5], exec
	s_cselect_b32 s25, s7, s31
	s_cselect_b32 s24, s6, s30
	s_add_u32 s60, s26, 0x10000
	s_addc_u32 s61, s27, 0
	s_add_u32 s34, s26, 0x18000
	s_addc_u32 s35, s27, 0
	s_add_u32 s62, s26, 0xc000
	s_addc_u32 s63, s27, 0
	s_mov_b32 m0, s46
	ds_read_b128 v[32:35], v143
	ds_read_b128 v[36:39], v143 offset:1024
	ds_read_b128 v[40:43], v143 offset:2048
	ds_read_b128 v[44:47], v143 offset:3072
	ds_read_b128 v[48:51], v143 offset:4096
	ds_read_b128 v[52:55], v143 offset:5120
	ds_read_b128 v[56:59], v143 offset:6144
	ds_read_b128 v[60:63], v143 offset:7168
	global_load_lds_dwordx4 v134, s[62:63]
	v_lshl_add_u64 v[64:65], s[62:63], 0, v[130:131]
	s_mov_b32 m0, s47
	s_nop 0
	global_load_lds_dwordx4 v[64:65], off
	s_waitcnt vmcnt(8)
	s_waitcnt lgkmcnt(0)
	s_barrier
	s_waitcnt lgkmcnt(0)
	v_mfma_f32_16x16x32_bf16 v[64:67], v[0:3], v[32:35], 0
	v_mfma_f32_16x16x32_bf16 v[64:67], v[4:7], v[36:39], v[64:67]
	v_mfma_f32_16x16x32_bf16 v[68:71], v[8:11], v[32:35], 0
	v_mfma_f32_16x16x32_bf16 v[68:71], v[12:15], v[36:39], v[68:71]
	v_mfma_f32_16x16x32_bf16 v[72:75], v[0:3], v[40:43], 0
	v_mfma_f32_16x16x32_bf16 v[72:75], v[4:7], v[44:47], v[72:75]
	v_mfma_f32_16x16x32_bf16 v[76:79], v[8:11], v[40:43], 0
	v_mfma_f32_16x16x32_bf16 v[76:79], v[12:15], v[44:47], v[76:79]
	v_mfma_f32_16x16x32_bf16 v[80:83], v[0:3], v[48:51], 0
	v_mfma_f32_16x16x32_bf16 v[80:83], v[4:7], v[52:55], v[80:83]
	v_mfma_f32_16x16x32_bf16 v[84:87], v[8:11], v[48:51], 0
	v_mfma_f32_16x16x32_bf16 v[84:87], v[12:15], v[52:55], v[84:87]
	v_mfma_f32_16x16x32_bf16 v[88:91], v[0:3], v[56:59], 0
	v_mfma_f32_16x16x32_bf16 v[88:91], v[4:7], v[60:63], v[88:91]
	v_mfma_f32_16x16x32_bf16 v[92:95], v[8:11], v[56:59], 0
	v_mfma_f32_16x16x32_bf16 v[92:95], v[12:15], v[60:63], v[92:95]
	v_mfma_f32_16x16x32_bf16 v[96:99], v[16:19], v[32:35], 0
	v_mfma_f32_16x16x32_bf16 v[96:99], v[20:23], v[36:39], v[96:99]
	v_mfma_f32_16x16x32_bf16 v[32:35], v[24:27], v[32:35], 0
	v_mfma_f32_16x16x32_bf16 v[32:35], v[28:31], v[36:39], v[32:35]
	v_mfma_f32_16x16x32_bf16 v[36:39], v[16:19], v[40:43], 0
	v_mfma_f32_16x16x32_bf16 v[36:39], v[20:23], v[44:47], v[36:39]
	v_mfma_f32_16x16x32_bf16 v[40:43], v[24:27], v[40:43], 0
	v_mfma_f32_16x16x32_bf16 v[40:43], v[28:31], v[44:47], v[40:43]
	v_mfma_f32_16x16x32_bf16 v[44:47], v[16:19], v[48:51], 0
	v_mfma_f32_16x16x32_bf16 v[44:47], v[20:23], v[52:55], v[44:47]
	v_mfma_f32_16x16x32_bf16 v[48:51], v[24:27], v[48:51], 0
	v_mfma_f32_16x16x32_bf16 v[48:51], v[28:31], v[52:55], v[48:51]
	v_mfma_f32_16x16x32_bf16 v[52:55], v[16:19], v[56:59], 0
	v_mfma_f32_16x16x32_bf16 v[52:55], v[20:23], v[60:63], v[52:55]
	v_mfma_f32_16x16x32_bf16 v[56:59], v[24:27], v[56:59], 0
	v_mfma_f32_16x16x32_bf16 v[56:59], v[28:31], v[60:63], v[56:59]
	s_barrier
	v_lshl_add_u64 v[210:211], s[30:31], 0, v[132:133]
	s_mov_b32 m0, s48
	v_lshl_add_u64 v[146:147], v[210:211], 0, s[16:17]
	v_lshl_add_u64 v[212:213], s[30:31], 0, v[128:129]
	s_add_u32 s62, s30, 0x10100
	ds_read_b128 v[60:63], v143 offset:16384
	ds_read_b128 v[100:103], v143 offset:17408
	ds_read_b128 v[104:107], v143 offset:18432
	ds_read_b128 v[108:111], v143 offset:19456
	ds_read_b128 v[112:115], v143 offset:20480
	ds_read_b128 v[116:119], v143 offset:21504
	ds_read_b128 v[120:123], v143 offset:22528
	ds_read_b128 v[124:127], v143 offset:23552
	global_load_lds_dwordx4 v[146:147], off
	v_lshl_add_u64 v[146:147], v[212:213], 0, s[16:17]
	s_mov_b32 m0, s50
	s_addc_u32 s63, s31, 0
	global_load_lds_dwordx4 v[146:147], off
	s_mov_b32 m0, s51
	s_nop 0
	global_load_lds_dwordx4 v132, s[62:63]
	s_mov_b32 m0, s52
	s_nop 0
	global_load_lds_dwordx4 v128, s[62:63]
	s_mov_b32 m0, s23
	s_nop 0
	global_load_lds_dwordx4 v134, s[60:61]
	v_lshl_add_u64 v[146:147], s[60:61], 0, v[130:131]
	s_mov_b32 m0, s37
	s_nop 0
	global_load_lds_dwordx4 v[146:147], off
	s_waitcnt vmcnt(8)
	s_waitcnt lgkmcnt(0)
	s_barrier
; #define PG8_STAGE(bufoff, gbase, voff) do { _Pragma("unroll") for (int _i = 0; _i < 2; ++_i) \
;         __builtin_amdgcn_global_load_lds((const unsigned*)((const char*)(gbase) + (voff)[_i]), (PG8_LAS unsigned*)(lds + (bufoff) + ldsw + _i * 8192), 16, 0, 0); } while (0)
; #define PG8_LDA(dst, b, h) do { _Pragma("unroll") for (int m = 0; m < 4; ++m) _Pragma("unroll") for (int k = 0; k < 2; ++k) dst[m][k] = *(const PG8_LAS bf16x8*)(lds + PG8_SA(b, h) + aoff + m * 2048 + k * 1024); } while (0)
; #define PG8_LDB(dst, b, h) do { _Pragma("unroll") for (int n = 0; n < 2; ++n) _Pragma("unroll") for (int k = 0; k < 2; ++k) dst[n][k] = *(const PG8_LAS bf16x8*)(lds + PG8_SB(b, h) + boff + n * 2048 + k * 1024); } while (0)
; #define PG8_MMA(ai, bj, At, Bt) do { __builtin_amdgcn_s_setprio(1); _Pragma("unroll") for (int m = 0; m < 4; ++m) _Pragma("unroll") for (int n = 0; n < 2; ++n) _Pragma("unroll") for (int k = 0; k < 2; ++k) \
;         acc[ai][bj][m][n] = __builtin_amdgcn_mfma_f32_16x16x32_bf16(Bt[n][k], At[m][k], acc[ai][bj][m][n], 0, 0, 0); __builtin_amdgcn_s_setprio(0); } while (0)
; #define PG8_WAIT_V(n) asm volatile("s_waitcnt vmcnt(" #n ")" ::: "memory")
; #define PG8_WAIT_L(n) asm volatile("s_waitcnt lgkmcnt(" #n ")" ::: "memory")
; #define PG8_BAR __builtin_amdgcn_s_barrier()
; #define PG8_SCHED __builtin_amdgcn_sched_barrier(0)
;     ...
;             PG8_WAIT_V(8); PG8_WAIT_L(0); PG8_BAR; PG8_MMA(1, 0, At, B0); PG8_MMA(1, 1, At, B1); PG8_BAR; PG8_SCHED;
;             PG8_LDB(B0, 1, 0); PG8_LDB(B1, 1, 1); PG8_SCHED; PG8_LDA(At, 1, 0); PG8_STAGE(PG8_SA(0, 1), a2 + hstepA, voffA);
;             PG8_WAIT_V(8); PG8_WAIT_L(0); PG8_BAR; PG8_MMA(0, 0, At, B0); PG8_MMA(0, 1, At, B1); PG8_BAR; PG8_SCHED;
	s_waitcnt lgkmcnt(0)
	v_mfma_f32_16x16x32_bf16 v[146:149], v[0:3], v[60:63], 0
	v_mfma_f32_16x16x32_bf16 v[146:149], v[4:7], v[100:103], v[146:149]
	v_mfma_f32_16x16x32_bf16 v[154:157], v[0:3], v[104:107], 0
	v_mfma_f32_16x16x32_bf16 v[154:157], v[4:7], v[108:111], v[154:157]
	v_mfma_f32_16x16x32_bf16 v[162:165], v[0:3], v[112:115], 0
	v_mfma_f32_16x16x32_bf16 v[162:165], v[4:7], v[116:119], v[162:165]
	v_mfma_f32_16x16x32_bf16 v[0:3], v[0:3], v[120:123], 0
	v_mfma_f32_16x16x32_bf16 v[0:3], v[4:7], v[124:127], v[0:3]
	v_mfma_f32_16x16x32_bf16 v[4:7], v[8:11], v[120:123], 0
	v_mfma_f32_16x16x32_bf16 v[4:7], v[12:15], v[124:127], v[4:7]
	v_mfma_f32_16x16x32_bf16 v[150:153], v[8:11], v[60:63], 0
	v_mfma_f32_16x16x32_bf16 v[150:153], v[12:15], v[100:103], v[150:153]
	v_mfma_f32_16x16x32_bf16 v[158:161], v[8:11], v[104:107], 0
	v_mfma_f32_16x16x32_bf16 v[158:161], v[12:15], v[108:111], v[158:161]
	v_mfma_f32_16x16x32_bf16 v[166:169], v[8:11], v[112:115], 0
	v_mfma_f32_16x16x32_bf16 v[166:169], v[12:15], v[116:119], v[166:169]
	v_mfma_f32_16x16x32_bf16 v[8:11], v[16:19], v[60:63], 0
	v_mfma_f32_16x16x32_bf16 v[8:11], v[20:23], v[100:103], v[8:11]
	v_mfma_f32_16x16x32_bf16 v[12:15], v[24:27], v[60:63], 0
	v_mfma_f32_16x16x32_bf16 v[12:15], v[28:31], v[100:103], v[12:15]
	v_mfma_f32_16x16x32_bf16 v[60:63], v[16:19], v[104:107], 0
	v_mfma_f32_16x16x32_bf16 v[60:63], v[20:23], v[108:111], v[60:63]
	v_mfma_f32_16x16x32_bf16 v[100:103], v[24:27], v[104:107], 0
	v_mfma_f32_16x16x32_bf16 v[100:103], v[28:31], v[108:111], v[100:103]
	v_mfma_f32_16x16x32_bf16 v[104:107], v[16:19], v[112:115], 0
	v_mfma_f32_16x16x32_bf16 v[104:107], v[20:23], v[116:119], v[104:107]
	v_mfma_f32_16x16x32_bf16 v[16:19], v[16:19], v[120:123], 0
	v_mfma_f32_16x16x32_bf16 v[16:19], v[20:23], v[124:127], v[16:19]
	v_mfma_f32_16x16x32_bf16 v[108:111], v[24:27], v[112:115], 0
	v_mfma_f32_16x16x32_bf16 v[108:111], v[28:31], v[116:119], v[108:111]
	v_mfma_f32_16x16x32_bf16 v[20:23], v[24:27], v[120:123], 0
	v_mfma_f32_16x16x32_bf16 v[20:23], v[28:31], v[124:127], v[20:23]
	s_barrier
	ds_read_b128 v[24:27], v144
	ds_read_b128 v[28:31], v144 offset:1024
	ds_read_b128 v[112:115], v144 offset:2048
	ds_read_b128 v[116:119], v144 offset:3072
	ds_read_b128 v[120:123], v145
	ds_read_b128 v[124:127], v145 offset:1024
	ds_read_b128 v[170:173], v145 offset:2048
	ds_read_b128 v[174:177], v145 offset:3072
	s_add_u32 s60, s26, 0x14000
	s_addc_u32 s61, s27, 0
	s_mov_b32 m0, s39
	ds_read_b128 v[178:181], v143 offset:32768
	ds_read_b128 v[182:185], v143 offset:33792
	ds_read_b128 v[186:189], v143 offset:34816
	ds_read_b128 v[190:193], v143 offset:35840
	ds_read_b128 v[194:197], v143 offset:36864
	ds_read_b128 v[198:201], v143 offset:37888
	ds_read_b128 v[202:205], v143 offset:38912
	ds_read_b128 v[206:209], v143 offset:39936
	global_load_lds_dwordx4 v134, s[60:61]
	v_lshl_add_u64 v[214:215], s[60:61], 0, v[130:131]
	s_mov_b32 m0, s40
	s_nop 0
	global_load_lds_dwordx4 v[214:215], off
	s_waitcnt vmcnt(8)
	s_waitcnt lgkmcnt(0)
	s_barrier
	s_waitcnt lgkmcnt(0)
	v_mfma_f32_16x16x32_bf16 v[64:67], v[24:27], v[178:181], v[64:67]
	v_mfma_f32_16x16x32_bf16 v[64:67], v[28:31], v[182:185], v[64:67]
	v_mfma_f32_16x16x32_bf16 v[68:71], v[116:119], v[182:185], v[68:71]
	v_mfma_f32_16x16x32_bf16 v[68:71], v[112:115], v[178:181], v[68:71]
	v_mfma_f32_16x16x32_bf16 v[76:79], v[112:115], v[186:189], v[76:79]
	v_mfma_f32_16x16x32_bf16 v[76:79], v[116:119], v[190:193], v[76:79]
	v_mfma_f32_16x16x32_bf16 v[72:75], v[28:31], v[190:193], v[72:75]
	v_mfma_f32_16x16x32_bf16 v[72:75], v[24:27], v[186:189], v[72:75]
	v_mfma_f32_16x16x32_bf16 v[80:83], v[24:27], v[194:197], v[80:83]
	v_mfma_f32_16x16x32_bf16 v[80:83], v[28:31], v[198:201], v[80:83]
	v_mfma_f32_16x16x32_bf16 v[84:87], v[116:119], v[198:201], v[84:87]
	v_mfma_f32_16x16x32_bf16 v[84:87], v[112:115], v[194:197], v[84:87]
	v_mfma_f32_16x16x32_bf16 v[92:95], v[112:115], v[202:205], v[92:95]
	v_mfma_f32_16x16x32_bf16 v[92:95], v[116:119], v[206:209], v[92:95]
	v_mfma_f32_16x16x32_bf16 v[88:91], v[28:31], v[206:209], v[88:91]
	v_mfma_f32_16x16x32_bf16 v[88:91], v[24:27], v[202:205], v[88:91]
	v_mfma_f32_16x16x32_bf16 v[96:99], v[120:123], v[178:181], v[96:99]
	v_mfma_f32_16x16x32_bf16 v[96:99], v[124:127], v[182:185], v[96:99]
	v_mfma_f32_16x16x32_bf16 v[32:35], v[174:177], v[182:185], v[32:35]
	v_mfma_f32_16x16x32_bf16 v[32:35], v[170:173], v[178:181], v[32:35]
	v_mfma_f32_16x16x32_bf16 v[40:43], v[170:173], v[186:189], v[40:43]
	v_mfma_f32_16x16x32_bf16 v[40:43], v[174:177], v[190:193], v[40:43]
	v_mfma_f32_16x16x32_bf16 v[36:39], v[124:127], v[190:193], v[36:39]
	v_mfma_f32_16x16x32_bf16 v[36:39], v[120:123], v[186:189], v[36:39]
	v_mfma_f32_16x16x32_bf16 v[44:47], v[120:123], v[194:197], v[44:47]
	v_mfma_f32_16x16x32_bf16 v[44:47], v[124:127], v[198:201], v[44:47]
	v_mfma_f32_16x16x32_bf16 v[48:51], v[174:177], v[198:201], v[48:51]
	v_mfma_f32_16x16x32_bf16 v[48:51], v[170:173], v[194:197], v[48:51]
	v_mfma_f32_16x16x32_bf16 v[56:59], v[170:173], v[202:205], v[56:59]
	v_mfma_f32_16x16x32_bf16 v[56:59], v[174:177], v[206:209], v[56:59]
	v_mfma_f32_16x16x32_bf16 v[52:55], v[124:127], v[206:209], v[52:55]
	v_mfma_f32_16x16x32_bf16 v[52:55], v[120:123], v[202:205], v[52:55]
	s_barrier
; #define PG8_STAGE(bufoff, gbase, voff) do { _Pragma("unroll") for (int _i = 0; _i < 2; ++_i) \
;         __builtin_amdgcn_global_load_lds((const unsigned*)((const char*)(gbase) + (voff)[_i]), (PG8_LAS unsigned*)(lds + (bufoff) + ldsw + _i * 8192), 16, 0, 0); } while (0)
; #define PG8_LDA(dst, b, h) do { _Pragma("unroll") for (int m = 0; m < 4; ++m) _Pragma("unroll") for (int k = 0; k < 2; ++k) dst[m][k] = *(const PG8_LAS bf16x8*)(lds + PG8_SA(b, h) + aoff + m * 2048 + k * 1024); } while (0)
; #define PG8_LDB(dst, b, h) do { _Pragma("unroll") for (int n = 0; n < 2; ++n) _Pragma("unroll") for (int k = 0; k < 2; ++k) dst[n][k] = *(const PG8_LAS bf16x8*)(lds + PG8_SB(b, h) + boff + n * 2048 + k * 1024); } while (0)
; #define PG8_MMA(ai, bj, At, Bt) do { __builtin_amdgcn_s_setprio(1); _Pragma("unroll") for (int m = 0; m < 4; ++m) _Pragma("unroll") for (int n = 0; n < 2; ++n) _Pragma("unroll") for (int k = 0; k < 2; ++k) \
;         acc[ai][bj][m][n] = __builtin_amdgcn_mfma_f32_16x16x32_bf16(Bt[n][k], At[m][k], acc[ai][bj][m][n], 0, 0, 0); __builtin_amdgcn_s_setprio(0); } while (0)
; #define PG8_WAIT_V(n) asm volatile("s_waitcnt vmcnt(" #n ")" ::: "memory")
; #define PG8_WAIT_L(n) asm volatile("s_waitcnt lgkmcnt(" #n ")" ::: "memory")
; #define PG8_BAR __builtin_amdgcn_s_barrier()
; #define PG8_SCHED __builtin_amdgcn_sched_barrier(0)
;     ...
;             PG8_LDB(B0, 0, 0); PG8_LDB(B1, 0, 1); PG8_SCHED; PG8_LDA(At, 0, 0); PG8_STAGE(PG8_SA(1, 1), a1 + hstepA, voffA);
;             PG8_WAIT_V(8); PG8_WAIT_L(0); PG8_BAR; PG8_MMA(0, 0, At, B0); PG8_MMA(0, 1, At, B1); PG8_BAR; PG8_SCHED;
;             PG8_LDA(At, 0, 1); PG8_STAGE(PG8_SB(0, 0), b2, voffB); PG8_STAGE(PG8_SB(0, 1), b2 + hstepB, voffB); PG8_STAGE(PG8_SA(0, 0), a2, voffA);
;             PG8_WAIT_V(8); PG8_WAIT_L(0); PG8_BAR; PG8_MMA(1, 0, At, B0); PG8_MMA(1, 1, At, B1); PG8_BAR; PG8_SCHED;
;             PG8_LDB(B0, 1, 0); PG8_LDB(B1, 1, 1); PG8_SCHED; PG8_LDA(At, 1, 0); PG8_STAGE(PG8_SA(0, 1), a2 + hstepA, voffA);
;             PG8_WAIT_V(8); PG8_WAIT_L(0); PG8_BAR; PG8_MMA(0, 0, At, B0); PG8_MMA(0, 1, At, B1); PG8_BAR; PG8_SCHED;
;             PG8_LDA(At, 1, 1); PG8_STAGE(PG8_SB(1, 0), b3, voffB); PG8_STAGE(PG8_SB(1, 1), b3 + hstepB, voffB); PG8_STAGE(PG8_SA(1, 0), a3, voffA);
;             PG8_WAIT_V(8); PG8_WAIT_L(0); PG8_BAR; PG8_MMA(1, 0, At, B0); PG8_MMA(1, 1, At, B1); PG8_BAR; PG8_SCHED;
	s_mov_b32 m0, s53
	v_lshl_add_u64 v[210:211], v[210:211], 0, s[18:19]
	s_add_u32 s30, s30, 0x10180
	ds_read_b128 v[178:181], v143 offset:49152
	ds_read_b128 v[182:185], v143 offset:50176
	ds_read_b128 v[186:189], v143 offset:51200
	ds_read_b128 v[190:193], v143 offset:52224
	ds_read_b128 v[194:197], v143 offset:53248
	ds_read_b128 v[198:201], v143 offset:54272
	ds_read_b128 v[202:205], v143 offset:55296
	ds_read_b128 v[206:209], v143 offset:56320
	global_load_lds_dwordx4 v[210:211], off
	v_lshl_add_u64 v[210:211], v[212:213], 0, s[18:19]
	s_mov_b32 m0, s54
	s_addc_u32 s31, s31, 0
	global_load_lds_dwordx4 v[210:211], off
	s_mov_b32 m0, s55
	s_nop 0
	global_load_lds_dwordx4 v132, s[30:31]
	s_mov_b32 m0, s56
	s_nop 0
	global_load_lds_dwordx4 v128, s[30:31]
	s_mov_b32 m0, s42
	s_nop 0
	global_load_lds_dwordx4 v134, s[34:35]
	s_mov_b32 m0, s43
	s_nop 0
	global_load_lds_dwordx4 v130, s[34:35]
	s_waitcnt vmcnt(8)
	s_waitcnt lgkmcnt(0)
	s_barrier
	s_waitcnt lgkmcnt(0)
	v_mfma_f32_16x16x32_bf16 v[0:3], v[24:27], v[202:205], v[0:3]
	v_mfma_f32_16x16x32_bf16 v[0:3], v[28:31], v[206:209], v[0:3]
	v_mfma_f32_16x16x32_bf16 v[4:7], v[116:119], v[206:209], v[4:7]
	v_mfma_f32_16x16x32_bf16 v[4:7], v[112:115], v[202:205], v[4:7]
	v_mfma_f32_16x16x32_bf16 v[150:153], v[112:115], v[178:181], v[150:153]
	v_mfma_f32_16x16x32_bf16 v[150:153], v[116:119], v[182:185], v[150:153]
	v_mfma_f32_16x16x32_bf16 v[146:149], v[28:31], v[182:185], v[146:149]
	v_mfma_f32_16x16x32_bf16 v[146:149], v[24:27], v[178:181], v[146:149]
	v_mfma_f32_16x16x32_bf16 v[154:157], v[24:27], v[186:189], v[154:157]
	v_mfma_f32_16x16x32_bf16 v[154:157], v[28:31], v[190:193], v[154:157]
	v_mfma_f32_16x16x32_bf16 v[158:161], v[116:119], v[190:193], v[158:161]
	v_mfma_f32_16x16x32_bf16 v[158:161], v[112:115], v[186:189], v[158:161]
	v_mfma_f32_16x16x32_bf16 v[166:169], v[112:115], v[194:197], v[166:169]
	v_mfma_f32_16x16x32_bf16 v[166:169], v[116:119], v[198:201], v[166:169]
	v_mfma_f32_16x16x32_bf16 v[162:165], v[28:31], v[198:201], v[162:165]
	v_mfma_f32_16x16x32_bf16 v[162:165], v[24:27], v[194:197], v[162:165]
	v_mfma_f32_16x16x32_bf16 v[8:11], v[120:123], v[178:181], v[8:11]
	v_mfma_f32_16x16x32_bf16 v[8:11], v[124:127], v[182:185], v[8:11]
	v_mfma_f32_16x16x32_bf16 v[12:15], v[170:173], v[178:181], v[12:15]
	v_mfma_f32_16x16x32_bf16 v[12:15], v[174:177], v[182:185], v[12:15]
	v_mfma_f32_16x16x32_bf16 v[24:27], v[120:123], v[186:189], v[60:63]
	v_mfma_f32_16x16x32_bf16 v[24:27], v[124:127], v[190:193], v[24:27]
	v_mfma_f32_16x16x32_bf16 v[28:31], v[170:173], v[186:189], v[100:103]
	v_mfma_f32_16x16x32_bf16 v[28:31], v[174:177], v[190:193], v[28:31]
	v_mfma_f32_16x16x32_bf16 v[60:63], v[120:123], v[194:197], v[104:107]
	v_mfma_f32_16x16x32_bf16 v[60:63], v[124:127], v[198:201], v[60:63]
	v_mfma_f32_16x16x32_bf16 v[100:103], v[170:173], v[194:197], v[108:111]
	v_mfma_f32_16x16x32_bf16 v[100:103], v[174:177], v[198:201], v[100:103]
	v_mfma_f32_16x16x32_bf16 v[16:19], v[120:123], v[202:205], v[16:19]
	v_mfma_f32_16x16x32_bf16 v[16:19], v[124:127], v[206:209], v[16:19]
	v_mfma_f32_16x16x32_bf16 v[20:23], v[170:173], v[202:205], v[20:23]
	v_mfma_f32_16x16x32_bf16 v[20:23], v[174:177], v[206:209], v[20:23]
	s_barrier
	ds_read_b128 v[104:107], v141
	ds_read_b128 v[108:111], v141 offset:1024
	ds_read_b128 v[112:115], v141 offset:2048
	ds_read_b128 v[116:119], v141 offset:3072
	ds_read_b128 v[120:123], v142
	ds_read_b128 v[124:127], v142 offset:1024
	ds_read_b128 v[170:173], v142 offset:2048
	ds_read_b128 v[174:177], v142 offset:3072
	s_add_u32 s30, s28, 0x8000
	s_addc_u32 s31, s29, 0
	s_add_u32 s26, s26, 0x1c000
	s_addc_u32 s27, s27, 0
	s_mov_b32 m0, s46
	ds_read_b128 v[178:181], v143
	ds_read_b128 v[182:185], v143 offset:1024
	ds_read_b128 v[186:189], v143 offset:2048
	ds_read_b128 v[190:193], v143 offset:3072
	ds_read_b128 v[194:197], v143 offset:4096
	ds_read_b128 v[198:201], v143 offset:5120
	ds_read_b128 v[202:205], v143 offset:6144
	ds_read_b128 v[206:209], v143 offset:7168
	global_load_lds_dwordx4 v134, s[26:27]
	v_lshl_add_u64 v[210:211], s[26:27], 0, v[130:131]
	s_mov_b32 m0, s47
	s_nop 0
	global_load_lds_dwordx4 v[210:211], off
	s_waitcnt vmcnt(8)
	s_waitcnt lgkmcnt(0)
	s_barrier
	s_waitcnt lgkmcnt(0)
	v_mfma_f32_16x16x32_bf16 v[64:67], v[104:107], v[178:181], v[64:67]
	v_mfma_f32_16x16x32_bf16 v[64:67], v[108:111], v[182:185], v[64:67]
	v_mfma_f32_16x16x32_bf16 v[68:71], v[112:115], v[178:181], v[68:71]
	v_mfma_f32_16x16x32_bf16 v[68:71], v[116:119], v[182:185], v[68:71]
	v_mfma_f32_16x16x32_bf16 v[72:75], v[104:107], v[186:189], v[72:75]
	v_mfma_f32_16x16x32_bf16 v[72:75], v[108:111], v[190:193], v[72:75]
	v_mfma_f32_16x16x32_bf16 v[76:79], v[112:115], v[186:189], v[76:79]
	v_mfma_f32_16x16x32_bf16 v[76:79], v[116:119], v[190:193], v[76:79]
	v_mfma_f32_16x16x32_bf16 v[80:83], v[104:107], v[194:197], v[80:83]
	v_mfma_f32_16x16x32_bf16 v[80:83], v[108:111], v[198:201], v[80:83]
	v_mfma_f32_16x16x32_bf16 v[84:87], v[112:115], v[194:197], v[84:87]
	v_mfma_f32_16x16x32_bf16 v[84:87], v[116:119], v[198:201], v[84:87]
	v_mfma_f32_16x16x32_bf16 v[88:91], v[104:107], v[202:205], v[88:91]
	v_mfma_f32_16x16x32_bf16 v[210:213], v[108:111], v[206:209], v[88:91]
	v_mfma_f32_16x16x32_bf16 v[88:91], v[112:115], v[202:205], v[92:95]
	v_mfma_f32_16x16x32_bf16 v[214:217], v[116:119], v[206:209], v[88:91]
	v_mfma_f32_16x16x32_bf16 v[88:91], v[120:123], v[178:181], v[96:99]
	v_mfma_f32_16x16x32_bf16 v[96:99], v[124:127], v[182:185], v[88:91]
	v_mfma_f32_16x16x32_bf16 v[32:35], v[170:173], v[178:181], v[32:35]
	v_mfma_f32_16x16x32_bf16 v[32:35], v[174:177], v[182:185], v[32:35]
	v_mfma_f32_16x16x32_bf16 v[36:39], v[120:123], v[186:189], v[36:39]
	v_mfma_f32_16x16x32_bf16 v[36:39], v[124:127], v[190:193], v[36:39]
	v_mfma_f32_16x16x32_bf16 v[40:43], v[170:173], v[186:189], v[40:43]
	v_mfma_f32_16x16x32_bf16 v[40:43], v[174:177], v[190:193], v[40:43]
	v_mfma_f32_16x16x32_bf16 v[44:47], v[120:123], v[194:197], v[44:47]
	v_mfma_f32_16x16x32_bf16 v[44:47], v[124:127], v[198:201], v[44:47]
	v_mfma_f32_16x16x32_bf16 v[48:51], v[170:173], v[194:197], v[48:51]
	v_mfma_f32_16x16x32_bf16 v[48:51], v[174:177], v[198:201], v[48:51]
	v_mfma_f32_16x16x32_bf16 v[52:55], v[120:123], v[202:205], v[52:55]
	v_mfma_f32_16x16x32_bf16 v[52:55], v[124:127], v[206:209], v[52:55]
	v_mfma_f32_16x16x32_bf16 v[56:59], v[170:173], v[202:205], v[56:59]
	v_mfma_f32_16x16x32_bf16 v[56:59], v[174:177], v[206:209], v[56:59]
	s_barrier
; #define PG8_STAGE(bufoff, gbase, voff) do { _Pragma("unroll") for (int _i = 0; _i < 2; ++_i) \
;         __builtin_amdgcn_global_load_lds((const unsigned*)((const char*)(gbase) + (voff)[_i]), (PG8_LAS unsigned*)(lds + (bufoff) + ldsw + _i * 8192), 16, 0, 0); } while (0)
; #define PG8_LDA(dst, b, h) do { _Pragma("unroll") for (int m = 0; m < 4; ++m) _Pragma("unroll") for (int k = 0; k < 2; ++k) dst[m][k] = *(const PG8_LAS bf16x8*)(lds + PG8_SA(b, h) + aoff + m * 2048 + k * 1024); } while (0)
; #define PG8_LDB(dst, b, h) do { _Pragma("unroll") for (int n = 0; n < 2; ++n) _Pragma("unroll") for (int k = 0; k < 2; ++k) dst[n][k] = *(const PG8_LAS bf16x8*)(lds + PG8_SB(b, h) + boff + n * 2048 + k * 1024); } while (0)
; #define PG8_MMA(ai, bj, At, Bt) do { __builtin_amdgcn_s_setprio(1); _Pragma("unroll") for (int m = 0; m < 4; ++m) _Pragma("unroll") for (int n = 0; n < 2; ++n) _Pragma("unroll") for (int k = 0; k < 2; ++k) \
;         acc[ai][bj][m][n] = __builtin_amdgcn_mfma_f32_16x16x32_bf16(Bt[n][k], At[m][k], acc[ai][bj][m][n], 0, 0, 0); __builtin_amdgcn_s_setprio(0); } while (0)
; #define PG8_WAIT_V(n) asm volatile("s_waitcnt vmcnt(" #n ")" ::: "memory")
; #define PG8_WAIT_L(n) asm volatile("s_waitcnt lgkmcnt(" #n ")" ::: "memory")
; #define PG8_BAR __builtin_amdgcn_s_barrier()
; #define PG8_SCHED __builtin_amdgcn_sched_barrier(0)
;     ...
;             PG8_LDA(At, 0, 1); PG8_STAGE(PG8_SB(0, 0), b2, voffB); PG8_STAGE(PG8_SB(0, 1), b2 + hstepB, voffB); PG8_STAGE(PG8_SA(0, 0), a2, voffA);
;             PG8_WAIT_V(8); PG8_WAIT_L(0); PG8_BAR; PG8_MMA(1, 0, At, B0); PG8_MMA(1, 1, At, B1); PG8_BAR; PG8_SCHED;
;             PG8_LDB(B0, 1, 0); PG8_LDB(B1, 1, 1); PG8_SCHED; PG8_LDA(At, 1, 0); PG8_STAGE(PG8_SA(0, 1), a2 + hstepA, voffA);
	s_mov_b32 m0, s48
	v_lshl_add_u64 v[246:247], s[24:25], 0, v[132:133]
	s_add_u32 s26, s24, 0x10000
	ds_read_b128 v[88:91], v143 offset:16384
	ds_read_b128 v[92:95], v143 offset:17408
	ds_read_b128 v[178:181], v143 offset:18432
	ds_read_b128 v[182:185], v143 offset:19456
	ds_read_b128 v[186:189], v143 offset:20480
	ds_read_b128 v[190:193], v143 offset:21504
	ds_read_b128 v[194:197], v143 offset:22528
	ds_read_b128 v[198:201], v143 offset:23552
	global_load_lds_dwordx4 v[246:247], off
	v_lshl_add_u64 v[248:249], s[24:25], 0, v[128:129]
	s_mov_b32 m0, s50
	s_addc_u32 s27, s25, 0
	global_load_lds_dwordx4 v[248:249], off
	s_mov_b32 m0, s51
	s_nop 0
	global_load_lds_dwordx4 v132, s[26:27]
	s_mov_b32 m0, s52
	s_nop 0
	global_load_lds_dwordx4 v128, s[26:27]
	s_mov_b32 m0, s23
	s_nop 0
	global_load_lds_dwordx4 v134, s[28:29]
	v_lshl_add_u64 v[202:203], s[28:29], 0, v[130:131]
	s_mov_b32 m0, s37
	s_nop 0
	global_load_lds_dwordx4 v[202:203], off
	s_waitcnt vmcnt(8)
	s_waitcnt lgkmcnt(0)
	s_barrier
	s_waitcnt lgkmcnt(0)
	v_mfma_f32_16x16x32_bf16 v[0:3], v[104:107], v[194:197], v[0:3]
	v_mfma_f32_16x16x32_bf16 v[0:3], v[108:111], v[198:201], v[0:3]
	v_mfma_f32_16x16x32_bf16 v[4:7], v[116:119], v[198:201], v[4:7]
	v_mfma_f32_16x16x32_bf16 v[4:7], v[112:115], v[194:197], v[4:7]
	v_mfma_f32_16x16x32_bf16 v[150:153], v[112:115], v[88:91], v[150:153]
	v_mfma_f32_16x16x32_bf16 v[150:153], v[116:119], v[92:95], v[150:153]
	v_mfma_f32_16x16x32_bf16 v[146:149], v[108:111], v[92:95], v[146:149]
	v_mfma_f32_16x16x32_bf16 v[146:149], v[104:107], v[88:91], v[146:149]
	v_mfma_f32_16x16x32_bf16 v[154:157], v[104:107], v[178:181], v[154:157]
	v_mfma_f32_16x16x32_bf16 v[154:157], v[108:111], v[182:185], v[154:157]
	v_mfma_f32_16x16x32_bf16 v[158:161], v[116:119], v[182:185], v[158:161]
	v_mfma_f32_16x16x32_bf16 v[158:161], v[112:115], v[178:181], v[158:161]
	v_mfma_f32_16x16x32_bf16 v[166:169], v[112:115], v[186:189], v[166:169]
	v_mfma_f32_16x16x32_bf16 v[166:169], v[116:119], v[190:193], v[166:169]
	v_mfma_f32_16x16x32_bf16 v[162:165], v[108:111], v[190:193], v[162:165]
	v_mfma_f32_16x16x32_bf16 v[162:165], v[104:107], v[186:189], v[162:165]
	v_mfma_f32_16x16x32_bf16 v[8:11], v[120:123], v[88:91], v[8:11]
	v_mfma_f32_16x16x32_bf16 v[202:205], v[124:127], v[92:95], v[8:11]
	v_mfma_f32_16x16x32_bf16 v[8:11], v[170:173], v[88:91], v[12:15]
	v_mfma_f32_16x16x32_bf16 v[206:209], v[174:177], v[92:95], v[8:11]
	v_mfma_f32_16x16x32_bf16 v[8:11], v[120:123], v[178:181], v[24:27]
	v_mfma_f32_16x16x32_bf16 v[218:221], v[124:127], v[182:185], v[8:11]
	v_mfma_f32_16x16x32_bf16 v[8:11], v[170:173], v[178:181], v[28:31]
	v_mfma_f32_16x16x32_bf16 v[178:181], v[174:177], v[182:185], v[8:11]
	v_mfma_f32_16x16x32_bf16 v[8:11], v[120:123], v[186:189], v[60:63]
	v_mfma_f32_16x16x32_bf16 v[182:185], v[124:127], v[190:193], v[8:11]
	v_mfma_f32_16x16x32_bf16 v[8:11], v[170:173], v[186:189], v[100:103]
	v_mfma_f32_16x16x32_bf16 v[186:189], v[174:177], v[190:193], v[8:11]
	v_mfma_f32_16x16x32_bf16 v[8:11], v[120:123], v[194:197], v[16:19]
	v_mfma_f32_16x16x32_bf16 v[190:193], v[124:127], v[198:201], v[8:11]
	v_mfma_f32_16x16x32_bf16 v[8:11], v[170:173], v[194:197], v[20:23]
	v_mfma_f32_16x16x32_bf16 v[170:173], v[174:177], v[198:201], v[8:11]
	s_barrier
	s_nop 4
	ds_read_b128 v[8:11], v144
	ds_read_b128 v[12:15], v144 offset:1024
	ds_read_b128 v[16:19], v144 offset:2048
	ds_read_b128 v[20:23], v144 offset:3072
	ds_read_b128 v[174:177], v145
	ds_read_b128 v[194:197], v145 offset:1024
	ds_read_b128 v[198:201], v145 offset:2048
	ds_read_b128 v[222:225], v145 offset:3072
	s_add_u32 s26, s28, 0x4000
	s_addc_u32 s27, s29, 0
	s_mov_b32 m0, s39
	ds_read_b128 v[24:27], v143 offset:32768
	ds_read_b128 v[28:31], v143 offset:33792
	ds_read_b128 v[60:63], v143 offset:34816
	ds_read_b128 v[226:229], v143 offset:35840
	ds_read_b128 v[230:233], v143 offset:36864
	ds_read_b128 v[234:237], v143 offset:37888
	ds_read_b128 v[238:241], v143 offset:38912
	ds_read_b128 v[242:245], v143 offset:39936
	global_load_lds_dwordx4 v134, s[26:27]
	v_lshl_add_u64 v[88:89], s[26:27], 0, v[130:131]
	s_mov_b32 m0, s40
	s_nop 0
	global_load_lds_dwordx4 v[88:89], off
	s_waitcnt vmcnt(8)
	s_waitcnt lgkmcnt(0)
	s_barrier
; #define PG8_STAGE(bufoff, gbase, voff) do { _Pragma("unroll") for (int _i = 0; _i < 2; ++_i) \
;         __builtin_amdgcn_global_load_lds((const unsigned*)((const char*)(gbase) + (voff)[_i]), (PG8_LAS unsigned*)(lds + (bufoff) + ldsw + _i * 8192), 16, 0, 0); } while (0)
; #define PG8_LDA(dst, b, h) do { _Pragma("unroll") for (int m = 0; m < 4; ++m) _Pragma("unroll") for (int k = 0; k < 2; ++k) dst[m][k] = *(const PG8_LAS bf16x8*)(lds + PG8_SA(b, h) + aoff + m * 2048 + k * 1024); } while (0)
; #define PG8_MMA(ai, bj, At, Bt) do { __builtin_amdgcn_s_setprio(1); _Pragma("unroll") for (int m = 0; m < 4; ++m) _Pragma("unroll") for (int n = 0; n < 2; ++n) _Pragma("unroll") for (int k = 0; k < 2; ++k) \
;         acc[ai][bj][m][n] = __builtin_amdgcn_mfma_f32_16x16x32_bf16(Bt[n][k], At[m][k], acc[ai][bj][m][n], 0, 0, 0); __builtin_amdgcn_s_setprio(0); } while (0)
; #define PG8_WAIT_V(n) asm volatile("s_waitcnt vmcnt(" #n ")" ::: "memory")
; #define PG8_WAIT_L(n) asm volatile("s_waitcnt lgkmcnt(" #n ")" ::: "memory")
; #define PG8_BAR __builtin_amdgcn_s_barrier()
; #define PG8_SCHED __builtin_amdgcn_sched_barrier(0)
;     ...
;             PG8_WAIT_V(8); PG8_WAIT_L(0); PG8_BAR; PG8_MMA(0, 0, At, B0); PG8_MMA(0, 1, At, B1); PG8_BAR; PG8_SCHED;
;             PG8_LDA(At, 1, 1); PG8_STAGE(PG8_SB(1, 0), b3, voffB); PG8_STAGE(PG8_SB(1, 1), b3 + hstepB, voffB); PG8_STAGE(PG8_SA(1, 0), a3, voffA);
;             PG8_WAIT_V(8); PG8_WAIT_L(0); PG8_BAR; PG8_MMA(1, 0, At, B0); PG8_MMA(1, 1, At, B1); PG8_BAR; PG8_SCHED;
	s_waitcnt lgkmcnt(0)
	v_mfma_f32_16x16x32_bf16 v[64:67], v[8:11], v[24:27], v[64:67]
	v_mfma_f32_16x16x32_bf16 v[124:127], v[12:15], v[28:31], v[64:67]
	v_mfma_f32_16x16x32_bf16 v[64:67], v[16:19], v[24:27], v[68:71]
	v_mfma_f32_16x16x32_bf16 v[120:123], v[20:23], v[28:31], v[64:67]
	v_mfma_f32_16x16x32_bf16 v[64:67], v[8:11], v[60:63], v[72:75]
	v_mfma_f32_16x16x32_bf16 v[108:111], v[12:15], v[226:229], v[64:67]
	v_mfma_f32_16x16x32_bf16 v[64:67], v[16:19], v[60:63], v[76:79]
	v_mfma_f32_16x16x32_bf16 v[104:107], v[20:23], v[226:229], v[64:67]
	v_mfma_f32_16x16x32_bf16 v[64:67], v[8:11], v[230:233], v[80:83]
	v_mfma_f32_16x16x32_bf16 v[92:95], v[12:15], v[234:237], v[64:67]
	v_mfma_f32_16x16x32_bf16 v[64:67], v[16:19], v[230:233], v[84:87]
	v_mfma_f32_16x16x32_bf16 v[88:91], v[20:23], v[234:237], v[64:67]
	v_mfma_f32_16x16x32_bf16 v[64:67], v[8:11], v[238:241], v[210:213]
	v_mfma_f32_16x16x32_bf16 v[76:79], v[12:15], v[242:245], v[64:67]
	v_mfma_f32_16x16x32_bf16 v[64:67], v[16:19], v[238:241], v[214:217]
	v_mfma_f32_16x16x32_bf16 v[72:75], v[20:23], v[242:245], v[64:67]
	v_mfma_f32_16x16x32_bf16 v[64:67], v[174:177], v[24:27], v[96:99]
	v_mfma_f32_16x16x32_bf16 v[24:27], v[198:201], v[24:27], v[32:35]
	v_mfma_f32_16x16x32_bf16 v[112:115], v[222:225], v[28:31], v[24:27]
	v_mfma_f32_16x16x32_bf16 v[24:27], v[174:177], v[60:63], v[36:39]
	v_mfma_f32_16x16x32_bf16 v[100:103], v[194:197], v[226:229], v[24:27]
	v_mfma_f32_16x16x32_bf16 v[24:27], v[198:201], v[60:63], v[40:43]
	v_mfma_f32_16x16x32_bf16 v[96:99], v[222:225], v[226:229], v[24:27]
	v_mfma_f32_16x16x32_bf16 v[24:27], v[174:177], v[230:233], v[44:47]
	v_mfma_f32_16x16x32_bf16 v[84:87], v[194:197], v[234:237], v[24:27]
	v_mfma_f32_16x16x32_bf16 v[24:27], v[198:201], v[230:233], v[48:51]
	v_mfma_f32_16x16x32_bf16 v[80:83], v[222:225], v[234:237], v[24:27]
	v_mfma_f32_16x16x32_bf16 v[24:27], v[174:177], v[238:241], v[52:55]
	v_mfma_f32_16x16x32_bf16 v[60:63], v[194:197], v[242:245], v[24:27]
	v_mfma_f32_16x16x32_bf16 v[24:27], v[198:201], v[238:241], v[56:59]
	v_mfma_f32_16x16x32_bf16 v[116:119], v[194:197], v[28:31], v[64:67]
	v_mfma_f32_16x16x32_bf16 v[56:59], v[222:225], v[242:245], v[24:27]
	s_barrier
	s_mov_b32 m0, s53
	s_nop 2
	v_lshl_add_u64 v[24:25], v[246:247], 0, s[12:13]
	s_add_u32 s24, s24, 0x10080
	ds_read_b128 v[32:35], v143 offset:49152
	ds_read_b128 v[36:39], v143 offset:50176
	ds_read_b128 v[210:213], v143 offset:51200
	ds_read_b128 v[214:217], v143 offset:52224
	ds_read_b128 v[226:229], v143 offset:53248
	ds_read_b128 v[230:233], v143 offset:54272
	ds_read_b128 v[234:237], v143 offset:55296
	ds_read_b128 v[238:241], v143 offset:56320
	global_load_lds_dwordx4 v[24:25], off
	v_lshl_add_u64 v[24:25], v[248:249], 0, s[12:13]
	s_mov_b32 m0, s54
	s_addc_u32 s25, s25, 0
	global_load_lds_dwordx4 v[24:25], off
	s_mov_b32 m0, s55
	s_nop 0
	global_load_lds_dwordx4 v132, s[24:25]
	s_mov_b32 m0, s56
	s_nop 0
	global_load_lds_dwordx4 v128, s[24:25]
	s_mov_b32 m0, s42
	s_nop 0
	global_load_lds_dwordx4 v134, s[30:31]
	v_lshl_add_u64 v[24:25], s[30:31], 0, v[130:131]
	s_mov_b32 m0, s43
	s_nop 0
	global_load_lds_dwordx4 v[24:25], off
	s_waitcnt vmcnt(8)
	s_waitcnt lgkmcnt(0)
	s_barrier
	s_waitcnt lgkmcnt(0)
	v_mfma_f32_16x16x32_bf16 v[24:27], v[8:11], v[32:35], v[146:149]
	v_mfma_f32_16x16x32_bf16 v[68:71], v[12:15], v[36:39], v[24:27]
	v_mfma_f32_16x16x32_bf16 v[24:27], v[16:19], v[32:35], v[150:153]
	v_mfma_f32_16x16x32_bf16 v[64:67], v[20:23], v[36:39], v[24:27]
	v_mfma_f32_16x16x32_bf16 v[24:27], v[8:11], v[210:213], v[154:157]
	v_mfma_f32_16x16x32_bf16 v[44:47], v[12:15], v[214:217], v[24:27]
	v_mfma_f32_16x16x32_bf16 v[24:27], v[16:19], v[210:213], v[158:161]
	v_mfma_f32_16x16x32_bf16 v[40:43], v[20:23], v[214:217], v[24:27]
	v_mfma_f32_16x16x32_bf16 v[24:27], v[8:11], v[226:229], v[162:165]
	v_mfma_f32_16x16x32_bf16 v[28:31], v[12:15], v[230:233], v[24:27]
	v_mfma_f32_16x16x32_bf16 v[0:3], v[8:11], v[234:237], v[0:3]
	v_mfma_f32_16x16x32_bf16 v[12:15], v[12:15], v[238:241], v[0:3]
	v_mfma_f32_16x16x32_bf16 v[24:27], v[16:19], v[226:229], v[166:169]
	v_mfma_f32_16x16x32_bf16 v[24:27], v[20:23], v[230:233], v[24:27]
	v_mfma_f32_16x16x32_bf16 v[0:3], v[16:19], v[234:237], v[4:7]
	v_mfma_f32_16x16x32_bf16 v[8:11], v[20:23], v[238:241], v[0:3]
	v_mfma_f32_16x16x32_bf16 v[0:3], v[174:177], v[32:35], v[202:205]
	v_mfma_f32_16x16x32_bf16 v[52:55], v[194:197], v[36:39], v[0:3]
	v_mfma_f32_16x16x32_bf16 v[0:3], v[198:201], v[32:35], v[206:209]
	v_mfma_f32_16x16x32_bf16 v[48:51], v[222:225], v[36:39], v[0:3]
	v_mfma_f32_16x16x32_bf16 v[0:3], v[174:177], v[210:213], v[218:221]
	v_mfma_f32_16x16x32_bf16 v[36:39], v[194:197], v[214:217], v[0:3]
	v_mfma_f32_16x16x32_bf16 v[0:3], v[198:201], v[210:213], v[178:181]
	v_mfma_f32_16x16x32_bf16 v[32:35], v[222:225], v[214:217], v[0:3]
	v_mfma_f32_16x16x32_bf16 v[0:3], v[174:177], v[226:229], v[182:185]
	v_mfma_f32_16x16x32_bf16 v[20:23], v[194:197], v[230:233], v[0:3]
	v_mfma_f32_16x16x32_bf16 v[0:3], v[198:201], v[226:229], v[186:189]
	v_mfma_f32_16x16x32_bf16 v[16:19], v[222:225], v[230:233], v[0:3]
	v_mfma_f32_16x16x32_bf16 v[0:3], v[174:177], v[234:237], v[190:193]
	v_mfma_f32_16x16x32_bf16 v[4:7], v[194:197], v[238:241], v[0:3]
	v_mfma_f32_16x16x32_bf16 v[0:3], v[198:201], v[234:237], v[170:173]
	v_mfma_f32_16x16x32_bf16 v[0:3], v[222:225], v[238:241], v[0:3]
	s_barrier
	s_and_b64 vcc, exec, s[0:1]
	s_cbranch_vccnz .LBB0_99
	s_barrier

; #define PG8_STAGE(bufoff, gbase, voff) do { _Pragma("unroll") for (int _i = 0; _i < 2; ++_i) \
;         __builtin_amdgcn_global_load_lds((const unsigned*)((const char*)(gbase) + (voff)[_i]), (PG8_LAS unsigned*)(lds + (bufoff) + ldsw + _i * 8192), 16, 0, 0); } while (0)
; #define PG8_LDA(dst, b, h) do { _Pragma("unroll") for (int m = 0; m < 4; ++m) _Pragma("unroll") for (int k = 0; k < 2; ++k) dst[m][k] = *(const PG8_LAS bf16x8*)(lds + PG8_SA(b, h) + aoff + m * 2048 + k * 1024); } while (0)
; #define PG8_LDB(dst, b, h) do { _Pragma("unroll") for (int n = 0; n < 2; ++n) _Pragma("unroll") for (int k = 0; k < 2; ++k) dst[n][k] = *(const PG8_LAS bf16x8*)(lds + PG8_SB(b, h) + boff + n * 2048 + k * 1024); } while (0)
; #define PG8_MMA(ai, bj, At, Bt) do { __builtin_amdgcn_s_setprio(1); _Pragma("unroll") for (int m = 0; m < 4; ++m) _Pragma("unroll") for (int n = 0; n < 2; ++n) _Pragma("unroll") for (int k = 0; k < 2; ++k) \
;         acc[ai][bj][m][n] = __builtin_amdgcn_mfma_f32_16x16x32_bf16(Bt[n][k], At[m][k], acc[ai][bj][m][n], 0, 0, 0); __builtin_amdgcn_s_setprio(0); } while (0)
; #define PG8_WAIT_V(n) asm volatile("s_waitcnt vmcnt(" #n ")" ::: "memory")
; #define PG8_WAIT_L(n) asm volatile("s_waitcnt lgkmcnt(" #n ")" ::: "memory")
; #define PG8_BAR __builtin_amdgcn_s_barrier()
; #define PG8_SCHED __builtin_amdgcn_sched_barrier(0)
;     ...
;             const char* a1 = cA + (ptrdiff_t)(t + 1) * kstepA;
;             const char* a2 = last ? nA : cA + (ptrdiff_t)(t + 2) * kstepA; const char* b2 = last ? nB : cB + (ptrdiff_t)(t + 2) * kstep;
;             const char* a3 = a2 + kstepA; const char* b3 = b2 + kstep;
;             if (last && has_next) S.a_ready(nxt);
;             if constexpr (SP2) {
;             PG8_LDB(B0, 0, 0); PG8_LDB(B1, 0, 1); PG8_SCHED; PG8_LDA(At, 0, 0); PG8_STAGE(PG8_SA(1, 1), a1 + hstepA, voffA);
;             PG8_WAIT_V(8); PG8_WAIT_L(0); PG8_BAR; PG8_MMA(0, 0, At, B0); PG8_MMA(0, 1, At, B1); PG8_BAR; PG8_SCHED;
;             PG8_LDA(At, 0, 1); PG8_STAGE(PG8_SB(0, 0), b2, voffB); PG8_STAGE(PG8_SB(0, 1), b2 + hstepB, voffB); PG8_STAGE(PG8_SA(0, 0), a2, voffA);
;             PG8_WAIT_V(8); PG8_WAIT_L(0); PG8_BAR; PG8_MMA(1, 0, At, B0); PG8_MMA(1, 1, At, B1); PG8_BAR; PG8_SCHED;
.LBB0_328:
	s_add_u32 s65, s6, 0x4000
	s_addc_u32 s66, s7, 0
	s_cmp_eq_u32 vcc_lo, 28
	s_cselect_b32 s90, s54, s65
	s_cselect_b32 s91, s29, s66
	s_cselect_b32 s88, s55, s56
	s_cselect_b32 s89, s31, s57
	s_add_u32 s86, s90, 0x8000
	s_addc_u32 s87, s91, 0
	s_add_i32 s65, 0, 0x10000
	s_add_i32 s66, 0, 0x14000
	v_add_u32_e32 v22, s65, v182
	v_add_u32_e32 v54, s66, v182
	ds_read_b128 v[10:13], v22
	ds_read_b128 v[14:17], v22 offset:1024
	ds_read_b128 v[18:21], v22 offset:2048
	ds_read_b128 v[22:25], v22 offset:3072
	ds_read_b128 v[26:29], v54
	ds_read_b128 v[38:41], v54 offset:1024
	ds_read_b128 v[50:53], v54 offset:2048
	ds_read_b128 v[54:57], v54 offset:3072
	s_add_i32 m0, s51, 0xc000
	ds_read_b128 v[172:175], v183
	ds_read_b128 v[176:179], v183 offset:1024
	ds_read_b128 v[184:187], v183 offset:2048
	ds_read_b128 v[188:191], v183 offset:3072
	ds_read_b128 v[192:195], v183 offset:4096
	ds_read_b128 v[196:199], v183 offset:5120
	ds_read_b128 v[200:203], v183 offset:6144
	ds_read_b128 v[204:207], v183 offset:7168
	global_load_lds_dwordx4 v168, s[6:7]
	s_add_i32 m0, s51, 0xe000
	s_nop 0
	global_load_lds_dwordx4 v170, s[6:7]
	s_waitcnt vmcnt(8)
	s_waitcnt lgkmcnt(0)
	s_barrier
	s_waitcnt lgkmcnt(0)
	v_mfma_f32_16x16x32_bf16 v[158:161], v[10:13], v[172:175], v[158:161]
	v_mfma_f32_16x16x32_bf16 v[158:161], v[14:17], v[176:179], v[158:161]
	v_mfma_f32_16x16x32_bf16 v[154:157], v[22:25], v[176:179], v[154:157]
	v_mfma_f32_16x16x32_bf16 v[154:157], v[18:21], v[172:175], v[154:157]
	v_mfma_f32_16x16x32_bf16 v[138:141], v[18:21], v[184:187], v[138:141]
	v_mfma_f32_16x16x32_bf16 v[138:141], v[22:25], v[188:191], v[138:141]
	v_mfma_f32_16x16x32_bf16 v[142:145], v[14:17], v[188:191], v[142:145]
	v_mfma_f32_16x16x32_bf16 v[142:145], v[10:13], v[184:187], v[142:145]
	v_mfma_f32_16x16x32_bf16 v[126:129], v[10:13], v[192:195], v[126:129]
	v_mfma_f32_16x16x32_bf16 v[126:129], v[14:17], v[196:199], v[126:129]
	v_mfma_f32_16x16x32_bf16 v[122:125], v[22:25], v[196:199], v[122:125]
	v_mfma_f32_16x16x32_bf16 v[122:125], v[18:21], v[192:195], v[122:125]
	v_mfma_f32_16x16x32_bf16 v[106:109], v[18:21], v[200:203], v[106:109]
	v_mfma_f32_16x16x32_bf16 v[106:109], v[22:25], v[204:207], v[106:109]
	v_mfma_f32_16x16x32_bf16 v[110:113], v[14:17], v[204:207], v[110:113]
	v_mfma_f32_16x16x32_bf16 v[110:113], v[10:13], v[200:203], v[110:113]
	v_mfma_f32_16x16x32_bf16 v[150:153], v[26:29], v[172:175], v[150:153]
	v_mfma_f32_16x16x32_bf16 v[150:153], v[38:41], v[176:179], v[150:153]
	v_mfma_f32_16x16x32_bf16 v[146:149], v[54:57], v[176:179], v[146:149]
	v_mfma_f32_16x16x32_bf16 v[146:149], v[50:53], v[172:175], v[146:149]
	v_mfma_f32_16x16x32_bf16 v[130:133], v[50:53], v[184:187], v[130:133]
	v_mfma_f32_16x16x32_bf16 v[130:133], v[54:57], v[188:191], v[130:133]
	v_mfma_f32_16x16x32_bf16 v[134:137], v[38:41], v[188:191], v[134:137]
	v_mfma_f32_16x16x32_bf16 v[134:137], v[26:29], v[184:187], v[134:137]
	v_mfma_f32_16x16x32_bf16 v[118:121], v[26:29], v[192:195], v[118:121]
	v_mfma_f32_16x16x32_bf16 v[118:121], v[38:41], v[196:199], v[118:121]
	v_mfma_f32_16x16x32_bf16 v[114:117], v[54:57], v[196:199], v[114:117]
	v_mfma_f32_16x16x32_bf16 v[114:117], v[50:53], v[192:195], v[114:117]
	v_mfma_f32_16x16x32_bf16 v[98:101], v[50:53], v[200:203], v[98:101]
	v_mfma_f32_16x16x32_bf16 v[98:101], v[54:57], v[204:207], v[98:101]
	v_mfma_f32_16x16x32_bf16 v[102:105], v[38:41], v[204:207], v[102:105]
	v_mfma_f32_16x16x32_bf16 v[102:105], v[26:29], v[200:203], v[102:105]
	s_barrier
	s_add_i32 s65, s65, s2
	s_mov_b32 m0, s65
	ds_read_b128 v[172:175], v183 offset:16384
	ds_read_b128 v[176:179], v183 offset:17408
	ds_read_b128 v[184:187], v183 offset:18432
	ds_read_b128 v[188:191], v183 offset:19456
	ds_read_b128 v[192:195], v183 offset:20480
	ds_read_b128 v[196:199], v183 offset:21504
	ds_read_b128 v[200:203], v183 offset:22528
	ds_read_b128 v[204:207], v183 offset:23552
	global_load_lds_dwordx4 v0, s[88:89]
	s_add_i32 m0, s65, 0x2000
	s_add_u32 s96, s88, 0x4000
	s_addc_u32 s97, s89, 0
	s_add_i32 s65, s66, s2
	global_load_lds_dwordx4 v162, s[88:89]
	s_mov_b32 m0, s65
	s_nop 0
	global_load_lds_dwordx4 v0, s[96:97]
	s_add_i32 m0, s65, 0x2000
	s_nop 0
	global_load_lds_dwordx4 v162, s[96:97]
	s_mov_b32 m0, s51
	s_nop 0
	global_load_lds_dwordx4 v166, s[90:91]
	s_mov_b32 m0, s92
	s_nop 0
	global_load_lds_dwordx4 v164, s[90:91]
	s_waitcnt vmcnt(8)
	s_waitcnt lgkmcnt(0)
	s_barrier
	s_waitcnt lgkmcnt(0)
	v_mfma_f32_16x16x32_bf16 v[94:97], v[10:13], v[172:175], v[94:97]
	v_mfma_f32_16x16x32_bf16 v[94:97], v[14:17], v[176:179], v[94:97]
	v_mfma_f32_16x16x32_bf16 v[90:93], v[18:21], v[172:175], v[90:93]
	v_mfma_f32_16x16x32_bf16 v[90:93], v[22:25], v[176:179], v[90:93]
	v_mfma_f32_16x16x32_bf16 v[78:81], v[10:13], v[184:187], v[78:81]
	v_mfma_f32_16x16x32_bf16 v[78:81], v[14:17], v[188:191], v[78:81]
	v_mfma_f32_16x16x32_bf16 v[74:77], v[18:21], v[184:187], v[74:77]
	v_mfma_f32_16x16x32_bf16 v[74:77], v[22:25], v[188:191], v[74:77]
	v_mfma_f32_16x16x32_bf16 v[62:65], v[10:13], v[192:195], v[62:65]
	v_mfma_f32_16x16x32_bf16 v[62:65], v[14:17], v[196:199], v[62:65]
	v_mfma_f32_16x16x32_bf16 v[58:61], v[18:21], v[192:195], v[58:61]
	v_mfma_f32_16x16x32_bf16 v[58:61], v[22:25], v[196:199], v[58:61]
	v_mfma_f32_16x16x32_bf16 v[10:13], v[10:13], v[200:203], v[34:37]
	v_mfma_f32_16x16x32_bf16 v[10:13], v[14:17], v[204:207], v[10:13]
	v_mfma_f32_16x16x32_bf16 v[14:17], v[18:21], v[200:203], v[30:33]
	v_mfma_f32_16x16x32_bf16 v[14:17], v[22:25], v[204:207], v[14:17]
	v_mfma_f32_16x16x32_bf16 v[30:33], v[26:29], v[184:187], v[70:73]
	v_mfma_f32_16x16x32_bf16 v[70:73], v[38:41], v[188:191], v[30:33]
	v_mfma_f32_16x16x32_bf16 v[30:33], v[50:53], v[184:187], v[66:69]
	v_mfma_f32_16x16x32_bf16 v[66:69], v[54:57], v[188:191], v[30:33]
	v_mfma_f32_16x16x32_bf16 v[30:33], v[26:29], v[192:195], v[46:49]
	v_mfma_f32_16x16x32_bf16 v[46:49], v[38:41], v[196:199], v[30:33]
	v_mfma_f32_16x16x32_bf16 v[30:33], v[50:53], v[192:195], v[42:45]
	v_mfma_f32_16x16x32_bf16 v[42:45], v[54:57], v[196:199], v[30:33]
	v_mfma_f32_16x16x32_bf16 v[6:9], v[26:29], v[200:203], v[6:9]
	v_mfma_f32_16x16x32_bf16 v[6:9], v[38:41], v[204:207], v[6:9]
	v_mfma_f32_16x16x32_bf16 v[2:5], v[50:53], v[200:203], v[2:5]
	v_mfma_f32_16x16x32_bf16 v[2:5], v[54:57], v[204:207], v[2:5]
	v_mfma_f32_16x16x32_bf16 v[18:21], v[26:29], v[172:175], v[86:89]
	v_mfma_f32_16x16x32_bf16 v[18:21], v[38:41], v[176:179], v[18:21]
	v_mfma_f32_16x16x32_bf16 v[22:25], v[50:53], v[172:175], v[82:85]
	v_mfma_f32_16x16x32_bf16 v[22:25], v[54:57], v[176:179], v[22:25]
	s_barrier
; #define PG8_STAGE(bufoff, gbase, voff) do { _Pragma("unroll") for (int _i = 0; _i < 2; ++_i) \
;         __builtin_amdgcn_global_load_lds((const unsigned*)((const char*)(gbase) + (voff)[_i]), (PG8_LAS unsigned*)(lds + (bufoff) + ldsw + _i * 8192), 16, 0, 0); } while (0)
; #define PG8_LDA(dst, b, h) do { _Pragma("unroll") for (int m = 0; m < 4; ++m) _Pragma("unroll") for (int k = 0; k < 2; ++k) dst[m][k] = *(const PG8_LAS bf16x8*)(lds + PG8_SA(b, h) + aoff + m * 2048 + k * 1024); } while (0)
; #define PG8_LDB(dst, b, h) do { _Pragma("unroll") for (int n = 0; n < 2; ++n) _Pragma("unroll") for (int k = 0; k < 2; ++k) dst[n][k] = *(const PG8_LAS bf16x8*)(lds + PG8_SB(b, h) + boff + n * 2048 + k * 1024); } while (0)
; #define PG8_MMA(ai, bj, At, Bt) do { __builtin_amdgcn_s_setprio(1); _Pragma("unroll") for (int m = 0; m < 4; ++m) _Pragma("unroll") for (int n = 0; n < 2; ++n) _Pragma("unroll") for (int k = 0; k < 2; ++k) \
;         acc[ai][bj][m][n] = __builtin_amdgcn_mfma_f32_16x16x32_bf16(Bt[n][k], At[m][k], acc[ai][bj][m][n], 0, 0, 0); __builtin_amdgcn_s_setprio(0); } while (0)
; #define PG8_WAIT_V(n) asm volatile("s_waitcnt vmcnt(" #n ")" ::: "memory")
; #define PG8_WAIT_L(n) asm volatile("s_waitcnt lgkmcnt(" #n ")" ::: "memory")
; #define PG8_BAR __builtin_amdgcn_s_barrier()
; #define PG8_SCHED __builtin_amdgcn_sched_barrier(0)
;     ...
;         for (int t = 0; t < nt; t += 2) {
;             const bool last = (t == nt - 2);
;     ...
;             PG8_LDB(B0, 1, 0); PG8_LDB(B1, 1, 1); PG8_SCHED; PG8_LDA(At, 1, 0); PG8_STAGE(PG8_SA(0, 1), a2 + hstepA, voffA);
;             PG8_WAIT_V(8); PG8_WAIT_L(0); PG8_BAR; PG8_MMA(0, 0, At, B0); PG8_MMA(0, 1, At, B1); PG8_BAR; PG8_SCHED;
;             PG8_LDA(At, 1, 1); PG8_STAGE(PG8_SB(1, 0), b3, voffB); PG8_STAGE(PG8_SB(1, 1), b3 + hstepB, voffB); PG8_STAGE(PG8_SA(1, 0), a3, voffA);
;             PG8_WAIT_V(8); PG8_WAIT_L(0); PG8_BAR; PG8_MMA(1, 0, At, B0); PG8_MMA(1, 1, At, B1); PG8_BAR; PG8_SCHED;
	s_add_i32 s65, 0, 0x18000
	v_add_u32_e32 v34, s65, v182
	s_add_i32 s66, 0, 0x1c000
	ds_read_b128 v[26:29], v34
	ds_read_b128 v[30:33], v34 offset:1024
	ds_read_b128 v[38:41], v34 offset:2048
	ds_read_b128 v[50:53], v34 offset:3072
	v_add_u32_e32 v34, s66, v182
	ds_read_b128 v[54:57], v34
	ds_read_b128 v[172:175], v34 offset:1024
	ds_read_b128 v[176:179], v34 offset:2048
	ds_read_b128 v[184:187], v34 offset:3072
	s_add_u32 s90, s90, 0x4000
	s_addc_u32 s91, s91, 0
	s_mov_b32 m0, s14
	ds_read_b128 v[34:37], v183 offset:32768
	ds_read_b128 v[82:85], v183 offset:33792
	ds_read_b128 v[86:89], v183 offset:34816
	ds_read_b128 v[188:191], v183 offset:35840
	ds_read_b128 v[192:195], v183 offset:36864
	ds_read_b128 v[196:199], v183 offset:37888
	ds_read_b128 v[200:203], v183 offset:38912
	ds_read_b128 v[204:207], v183 offset:39936
	global_load_lds_dwordx4 v166, s[90:91]
	v_lshl_add_u64 v[208:209], s[90:91], 0, v[164:165]
	s_mov_b32 m0, s15
	s_nop 0
	global_load_lds_dwordx4 v[208:209], off
	s_waitcnt vmcnt(8)
	s_waitcnt lgkmcnt(0)
	s_barrier
	s_waitcnt lgkmcnt(0)
	v_mfma_f32_16x16x32_bf16 v[158:161], v[26:29], v[34:37], v[158:161]
	v_mfma_f32_16x16x32_bf16 v[158:161], v[30:33], v[82:85], v[158:161]
	v_mfma_f32_16x16x32_bf16 v[154:157], v[50:53], v[82:85], v[154:157]
	v_mfma_f32_16x16x32_bf16 v[154:157], v[38:41], v[34:37], v[154:157]
	v_mfma_f32_16x16x32_bf16 v[138:141], v[38:41], v[86:89], v[138:141]
	v_mfma_f32_16x16x32_bf16 v[138:141], v[50:53], v[188:191], v[138:141]
	v_mfma_f32_16x16x32_bf16 v[142:145], v[30:33], v[188:191], v[142:145]
	v_mfma_f32_16x16x32_bf16 v[142:145], v[26:29], v[86:89], v[142:145]
	v_mfma_f32_16x16x32_bf16 v[126:129], v[26:29], v[192:195], v[126:129]
	v_mfma_f32_16x16x32_bf16 v[126:129], v[30:33], v[196:199], v[126:129]
	v_mfma_f32_16x16x32_bf16 v[122:125], v[50:53], v[196:199], v[122:125]
	v_mfma_f32_16x16x32_bf16 v[122:125], v[38:41], v[192:195], v[122:125]
	v_mfma_f32_16x16x32_bf16 v[106:109], v[38:41], v[200:203], v[106:109]
	v_mfma_f32_16x16x32_bf16 v[106:109], v[50:53], v[204:207], v[106:109]
	v_mfma_f32_16x16x32_bf16 v[110:113], v[30:33], v[204:207], v[110:113]
	v_mfma_f32_16x16x32_bf16 v[110:113], v[26:29], v[200:203], v[110:113]
	v_mfma_f32_16x16x32_bf16 v[150:153], v[54:57], v[34:37], v[150:153]
	v_mfma_f32_16x16x32_bf16 v[150:153], v[172:175], v[82:85], v[150:153]
	v_mfma_f32_16x16x32_bf16 v[34:37], v[176:179], v[34:37], v[146:149]
	v_mfma_f32_16x16x32_bf16 v[146:149], v[184:187], v[82:85], v[34:37]
	v_mfma_f32_16x16x32_bf16 v[34:37], v[54:57], v[86:89], v[134:137]
	v_mfma_f32_16x16x32_bf16 v[134:137], v[172:175], v[188:191], v[34:37]
	v_mfma_f32_16x16x32_bf16 v[34:37], v[176:179], v[86:89], v[130:133]
	v_mfma_f32_16x16x32_bf16 v[130:133], v[184:187], v[188:191], v[34:37]
	v_mfma_f32_16x16x32_bf16 v[34:37], v[54:57], v[192:195], v[118:121]
	v_mfma_f32_16x16x32_bf16 v[118:121], v[172:175], v[196:199], v[34:37]
	v_mfma_f32_16x16x32_bf16 v[34:37], v[176:179], v[192:195], v[114:117]
	v_mfma_f32_16x16x32_bf16 v[114:117], v[184:187], v[196:199], v[34:37]
	v_mfma_f32_16x16x32_bf16 v[34:37], v[54:57], v[200:203], v[102:105]
	v_mfma_f32_16x16x32_bf16 v[102:105], v[172:175], v[204:207], v[34:37]
	v_mfma_f32_16x16x32_bf16 v[34:37], v[176:179], v[200:203], v[98:101]
	v_mfma_f32_16x16x32_bf16 v[98:101], v[184:187], v[204:207], v[34:37]
	s_barrier
	s_add_u32 s90, s88, 0x8000
	s_addc_u32 s91, s89, 0
	s_add_i32 s65, s65, s2
	s_nop 0
	s_mov_b32 m0, s65
	ds_read_b128 v[82:85], v183 offset:49152
	ds_read_b128 v[188:191], v183 offset:50176
	ds_read_b128 v[192:195], v183 offset:51200
	ds_read_b128 v[196:199], v183 offset:52224
	ds_read_b128 v[200:203], v183 offset:53248
	ds_read_b128 v[204:207], v183 offset:54272
	ds_read_b128 v[208:211], v183 offset:55296
	ds_read_b128 v[216:219], v183 offset:56320
	global_load_lds_dwordx4 v0, s[90:91]
	s_add_i32 m0, s65, 0x2000
	s_add_u32 s88, s88, 0xc000
	s_addc_u32 s89, s89, 0
	s_add_i32 s65, s66, s2
	global_load_lds_dwordx4 v162, s[90:91]
	s_mov_b32 m0, s65
	s_nop 0
	global_load_lds_dwordx4 v0, s[88:89]
	s_add_i32 m0, s65, 0x2000
	s_nop 0
	global_load_lds_dwordx4 v162, s[88:89]
	s_mov_b32 m0, s71
	s_nop 0
	global_load_lds_dwordx4 v166, s[86:87]
	v_lshl_add_u64 v[34:35], s[86:87], 0, v[164:165]
	s_mov_b32 m0, s80
	s_nop 0
	global_load_lds_dwordx4 v[34:35], off
	s_waitcnt vmcnt(8)
	s_waitcnt lgkmcnt(0)
	s_barrier
	s_waitcnt lgkmcnt(0)
	v_mfma_f32_16x16x32_bf16 v[34:37], v[26:29], v[82:85], v[94:97]
	v_mfma_f32_16x16x32_bf16 v[94:97], v[30:33], v[188:191], v[34:37]
	v_mfma_f32_16x16x32_bf16 v[34:37], v[38:41], v[82:85], v[90:93]
	v_mfma_f32_16x16x32_bf16 v[90:93], v[50:53], v[188:191], v[34:37]
	v_mfma_f32_16x16x32_bf16 v[34:37], v[26:29], v[192:195], v[78:81]
	v_mfma_f32_16x16x32_bf16 v[78:81], v[30:33], v[196:199], v[34:37]
	v_mfma_f32_16x16x32_bf16 v[34:37], v[38:41], v[192:195], v[74:77]
	v_mfma_f32_16x16x32_bf16 v[74:77], v[50:53], v[196:199], v[34:37]
	v_mfma_f32_16x16x32_bf16 v[34:37], v[26:29], v[200:203], v[62:65]
	v_mfma_f32_16x16x32_bf16 v[62:65], v[30:33], v[204:207], v[34:37]
	v_mfma_f32_16x16x32_bf16 v[34:37], v[38:41], v[200:203], v[58:61]
	v_mfma_f32_16x16x32_bf16 v[58:61], v[50:53], v[204:207], v[34:37]
	v_mfma_f32_16x16x32_bf16 v[10:13], v[26:29], v[208:211], v[10:13]
	v_mfma_f32_16x16x32_bf16 v[34:37], v[30:33], v[216:219], v[10:13]
	v_mfma_f32_16x16x32_bf16 v[10:13], v[38:41], v[208:211], v[14:17]
	v_mfma_f32_16x16x32_bf16 v[30:33], v[50:53], v[216:219], v[10:13]
	v_mfma_f32_16x16x32_bf16 v[10:13], v[54:57], v[82:85], v[18:21]
	v_mfma_f32_16x16x32_bf16 v[86:89], v[172:175], v[188:191], v[10:13]
	v_mfma_f32_16x16x32_bf16 v[10:13], v[176:179], v[82:85], v[22:25]
	v_mfma_f32_16x16x32_bf16 v[82:85], v[184:187], v[188:191], v[10:13]
	v_mfma_f32_16x16x32_bf16 v[10:13], v[54:57], v[192:195], v[70:73]
	v_mfma_f32_16x16x32_bf16 v[70:73], v[172:175], v[196:199], v[10:13]
	v_mfma_f32_16x16x32_bf16 v[10:13], v[176:179], v[192:195], v[66:69]
	v_mfma_f32_16x16x32_bf16 v[66:69], v[184:187], v[196:199], v[10:13]
	v_mfma_f32_16x16x32_bf16 v[10:13], v[54:57], v[200:203], v[46:49]
	v_mfma_f32_16x16x32_bf16 v[46:49], v[172:175], v[204:207], v[10:13]
	v_mfma_f32_16x16x32_bf16 v[10:13], v[176:179], v[200:203], v[42:45]
	v_mfma_f32_16x16x32_bf16 v[42:45], v[184:187], v[204:207], v[10:13]
	v_mfma_f32_16x16x32_bf16 v[6:9], v[54:57], v[208:211], v[6:9]
	v_mfma_f32_16x16x32_bf16 v[6:9], v[172:175], v[216:219], v[6:9]
	v_mfma_f32_16x16x32_bf16 v[2:5], v[176:179], v[208:211], v[2:5]
	v_mfma_f32_16x16x32_bf16 v[2:5], v[184:187], v[216:219], v[2:5]
	s_barrier
	s_add_i32 vcc_lo, vcc_lo, 2
	s_add_u32 s6, s6, 0x10000
	s_addc_u32 s7, s7, 0
	s_add_u32 s56, s56, 0x10000
	s_addc_u32 s57, s57, 0
	s_cmp_gt_u32 vcc_lo, 29
	s_cbranch_scc0 .LBB0_328
	s_and_b64 vcc, exec, s[26:27]
	s_cbranch_vccz .LBB0_331
	s_barrier

; #define PG8_STAGE(bufoff, gbase, voff) do { _Pragma("unroll") for (int _i = 0; _i < 2; ++_i) \
;         __builtin_amdgcn_global_load_lds((const unsigned*)((const char*)(gbase) + (voff)[_i]), (PG8_LAS unsigned*)(lds + (bufoff) + ldsw + _i * 8192), 16, 0, 0); } while (0)
; #define PG8_LDA(dst, b, h) do { _Pragma("unroll") for (int m = 0; m < 4; ++m) _Pragma("unroll") for (int k = 0; k < 2; ++k) dst[m][k] = *(const PG8_LAS bf16x8*)(lds + PG8_SA(b, h) + aoff + m * 2048 + k * 1024); } while (0)
; #define PG8_LDB(dst, b, h) do { _Pragma("unroll") for (int n = 0; n < 2; ++n) _Pragma("unroll") for (int k = 0; k < 2; ++k) dst[n][k] = *(const PG8_LAS bf16x8*)(lds + PG8_SB(b, h) + boff + n * 2048 + k * 1024); } while (0)
; #define PG8_MMA(ai, bj, At, Bt) do { __builtin_amdgcn_s_setprio(1); _Pragma("unroll") for (int m = 0; m < 4; ++m) _Pragma("unroll") for (int n = 0; n < 2; ++n) _Pragma("unroll") for (int k = 0; k < 2; ++k) \
;         acc[ai][bj][m][n] = __builtin_amdgcn_mfma_f32_16x16x32_bf16(Bt[n][k], At[m][k], acc[ai][bj][m][n], 0, 0, 0); __builtin_amdgcn_s_setprio(0); } while (0)
; #define PG8_WAIT_V(n) asm volatile("s_waitcnt vmcnt(" #n ")" ::: "memory")
; #define PG8_WAIT_L(n) asm volatile("s_waitcnt lgkmcnt(" #n ")" ::: "memory")
; #define PG8_BAR __builtin_amdgcn_s_barrier()
; #define PG8_SCHED __builtin_amdgcn_sched_barrier(0)
;     ...
;             const char* a1 = cA + (ptrdiff_t)(t + 1) * kstepA;
;             const char* a2 = last ? nA : cA + (ptrdiff_t)(t + 2) * kstepA; const char* b2 = last ? nB : cB + (ptrdiff_t)(t + 2) * kstep;
;             const char* a3 = a2 + kstepA; const char* b3 = b2 + kstep;
;             if (last && has_next) S.a_ready(nxt);
;             if constexpr (SP2) {
;             PG8_LDB(B0, 0, 0); PG8_LDB(B1, 0, 1); PG8_SCHED; PG8_LDA(At, 0, 0); PG8_STAGE(PG8_SA(1, 1), a1 + hstepA, voffA);
;             PG8_WAIT_V(8); PG8_WAIT_L(0); PG8_BAR; PG8_MMA(0, 0, At, B0); PG8_MMA(0, 1, At, B1); PG8_BAR; PG8_SCHED;
;             PG8_LDA(At, 0, 1); PG8_STAGE(PG8_SB(0, 0), b2, voffB); PG8_STAGE(PG8_SB(0, 1), b2 + hstepB, voffB); PG8_STAGE(PG8_SA(0, 0), a2, voffA);
;             PG8_WAIT_V(8); PG8_WAIT_L(0); PG8_BAR; PG8_MMA(1, 0, At, B0); PG8_MMA(1, 1, At, B1); PG8_BAR; PG8_SCHED;
.LBB0_1128:
	s_add_u32 s36, s34, 0x4000
	s_addc_u32 s37, s35, 0
	s_cmp_eq_u32 s57, 28
	s_cselect_b32 s86, s29, s36
	s_cselect_b32 s87, s23, s37
	s_cselect_b32 s46, s31, s44
	s_cselect_b32 s47, s21, s56
	s_add_u32 s36, s86, 0x8000
	s_addc_u32 s37, s87, 0
	s_add_i32 s65, 0, 0x10000
	v_add_u32_e32 v0, s65, v242
	s_add_i32 s66, 0, 0x14000
	s_waitcnt lgkmcnt(0)
	ds_read_b128 v[130:133], v0
	ds_read_b128 v[134:137], v0 offset:1024
	ds_read_b128 v[138:141], v0 offset:2048
	ds_read_b128 v[142:145], v0 offset:3072
	v_add_u32_e32 v0, s66, v242
	ds_read_b128 v[146:149], v0
	ds_read_b128 v[150:153], v0 offset:1024
	ds_read_b128 v[154:157], v0 offset:2048
	ds_read_b128 v[158:161], v0 offset:3072
	s_add_i32 m0, s51, 0xc000
	ds_read_b128 v[162:165], v243
	ds_read_b128 v[166:169], v243 offset:1024
	ds_read_b128 v[170:173], v243 offset:2048
	ds_read_b128 v[174:177], v243 offset:3072
	ds_read_b128 v[178:181], v243 offset:4096
	ds_read_b128 v[182:185], v243 offset:5120
	ds_read_b128 v[198:201], v243 offset:6144
	ds_read_b128 v[202:205], v243 offset:7168
	global_load_lds_dwordx4 v194, s[34:35]
	s_add_i32 m0, s51, 0xe000
	s_nop 0
	global_load_lds_dwordx4 v196, s[34:35]
	s_waitcnt vmcnt(8)
	s_waitcnt lgkmcnt(0)
	s_barrier
	s_waitcnt lgkmcnt(0)
	v_mfma_f32_16x16x32_bf16 v[126:129], v[130:133], v[162:165], v[126:129]
	v_mfma_f32_16x16x32_bf16 v[126:129], v[134:137], v[166:169], v[126:129]
	v_mfma_f32_16x16x32_bf16 v[122:125], v[142:145], v[166:169], v[122:125]
	v_mfma_f32_16x16x32_bf16 v[122:125], v[138:141], v[162:165], v[122:125]
	v_mfma_f32_16x16x32_bf16 v[106:109], v[138:141], v[170:173], v[106:109]
	v_mfma_f32_16x16x32_bf16 v[106:109], v[142:145], v[174:177], v[106:109]
	v_mfma_f32_16x16x32_bf16 v[110:113], v[134:137], v[174:177], v[110:113]
	v_mfma_f32_16x16x32_bf16 v[110:113], v[130:133], v[170:173], v[110:113]
	v_mfma_f32_16x16x32_bf16 v[94:97], v[130:133], v[178:181], v[94:97]
	v_mfma_f32_16x16x32_bf16 v[94:97], v[134:137], v[182:185], v[94:97]
	v_mfma_f32_16x16x32_bf16 v[90:93], v[142:145], v[182:185], v[90:93]
	v_mfma_f32_16x16x32_bf16 v[90:93], v[138:141], v[178:181], v[90:93]
	v_mfma_f32_16x16x32_bf16 v[74:77], v[138:141], v[198:201], v[74:77]
	v_mfma_f32_16x16x32_bf16 v[74:77], v[142:145], v[202:205], v[74:77]
	v_mfma_f32_16x16x32_bf16 v[78:81], v[134:137], v[202:205], v[78:81]
	v_mfma_f32_16x16x32_bf16 v[78:81], v[130:133], v[198:201], v[78:81]
	v_mfma_f32_16x16x32_bf16 v[118:121], v[146:149], v[162:165], v[118:121]
	v_mfma_f32_16x16x32_bf16 v[118:121], v[150:153], v[166:169], v[118:121]
	v_mfma_f32_16x16x32_bf16 v[114:117], v[158:161], v[166:169], v[114:117]
	v_mfma_f32_16x16x32_bf16 v[114:117], v[154:157], v[162:165], v[114:117]
	v_mfma_f32_16x16x32_bf16 v[98:101], v[154:157], v[170:173], v[98:101]
	v_mfma_f32_16x16x32_bf16 v[98:101], v[158:161], v[174:177], v[98:101]
	v_mfma_f32_16x16x32_bf16 v[102:105], v[150:153], v[174:177], v[102:105]
	v_mfma_f32_16x16x32_bf16 v[102:105], v[146:149], v[170:173], v[102:105]
	v_mfma_f32_16x16x32_bf16 v[86:89], v[146:149], v[178:181], v[86:89]
	v_mfma_f32_16x16x32_bf16 v[86:89], v[150:153], v[182:185], v[86:89]
	v_mfma_f32_16x16x32_bf16 v[82:85], v[158:161], v[182:185], v[82:85]
	v_mfma_f32_16x16x32_bf16 v[82:85], v[154:157], v[178:181], v[82:85]
	v_mfma_f32_16x16x32_bf16 v[66:69], v[154:157], v[198:201], v[66:69]
	v_mfma_f32_16x16x32_bf16 v[66:69], v[158:161], v[202:205], v[66:69]
	v_mfma_f32_16x16x32_bf16 v[70:73], v[150:153], v[202:205], v[70:73]
	v_mfma_f32_16x16x32_bf16 v[70:73], v[146:149], v[198:201], v[70:73]
	s_barrier
	s_add_i32 s65, s65, s49
	s_mov_b32 m0, s65
	ds_read_b128 v[162:165], v243 offset:16384
	ds_read_b128 v[166:169], v243 offset:17408
	ds_read_b128 v[170:173], v243 offset:18432
	ds_read_b128 v[174:177], v243 offset:19456
	ds_read_b128 v[178:181], v243 offset:20480
	ds_read_b128 v[182:185], v243 offset:21504
	ds_read_b128 v[198:201], v243 offset:22528
	ds_read_b128 v[202:205], v243 offset:23552
	global_load_lds_dwordx4 v188, s[46:47]
	s_add_i32 m0, s65, 0x2000
	s_add_u32 s90, s46, 0x4000
	s_addc_u32 s91, s47, 0
	s_add_i32 s65, s66, s49
	global_load_lds_dwordx4 v192, s[46:47]
	s_mov_b32 m0, s65
	s_nop 0
	global_load_lds_dwordx4 v188, s[90:91]
	s_add_i32 m0, s65, 0x2000
	s_nop 0
	global_load_lds_dwordx4 v192, s[90:91]
	s_mov_b32 m0, s51
	s_nop 0
	global_load_lds_dwordx4 v186, s[86:87]
	s_mov_b32 m0, s54
	s_nop 0
	global_load_lds_dwordx4 v190, s[86:87]
	s_waitcnt vmcnt(8)
	s_waitcnt lgkmcnt(0)
	s_barrier
	s_waitcnt lgkmcnt(0)
	v_mfma_f32_16x16x32_bf16 v[62:65], v[130:133], v[162:165], v[62:65]
	v_mfma_f32_16x16x32_bf16 v[62:65], v[134:137], v[166:169], v[62:65]
	v_mfma_f32_16x16x32_bf16 v[58:61], v[142:145], v[166:169], v[58:61]
	v_mfma_f32_16x16x32_bf16 v[58:61], v[138:141], v[162:165], v[58:61]
	v_mfma_f32_16x16x32_bf16 v[42:45], v[138:141], v[170:173], v[42:45]
	v_mfma_f32_16x16x32_bf16 v[42:45], v[142:145], v[174:177], v[42:45]
	v_mfma_f32_16x16x32_bf16 v[46:49], v[134:137], v[174:177], v[46:49]
	v_mfma_f32_16x16x32_bf16 v[46:49], v[130:133], v[170:173], v[46:49]
	v_mfma_f32_16x16x32_bf16 v[30:33], v[130:133], v[178:181], v[30:33]
	v_mfma_f32_16x16x32_bf16 v[30:33], v[134:137], v[182:185], v[30:33]
	v_mfma_f32_16x16x32_bf16 v[26:29], v[142:145], v[182:185], v[26:29]
	v_mfma_f32_16x16x32_bf16 v[26:29], v[138:141], v[178:181], v[26:29]
	v_mfma_f32_16x16x32_bf16 v[10:13], v[138:141], v[198:201], v[10:13]
	v_mfma_f32_16x16x32_bf16 v[10:13], v[142:145], v[202:205], v[10:13]
	v_mfma_f32_16x16x32_bf16 v[14:17], v[134:137], v[202:205], v[14:17]
	v_mfma_f32_16x16x32_bf16 v[14:17], v[130:133], v[198:201], v[14:17]
	v_mfma_f32_16x16x32_bf16 v[54:57], v[146:149], v[162:165], v[54:57]
	v_mfma_f32_16x16x32_bf16 v[54:57], v[150:153], v[166:169], v[54:57]
	v_mfma_f32_16x16x32_bf16 v[50:53], v[158:161], v[166:169], v[50:53]
	v_mfma_f32_16x16x32_bf16 v[50:53], v[154:157], v[162:165], v[50:53]
	v_mfma_f32_16x16x32_bf16 v[34:37], v[154:157], v[170:173], v[34:37]
	v_mfma_f32_16x16x32_bf16 v[34:37], v[158:161], v[174:177], v[34:37]
	v_mfma_f32_16x16x32_bf16 v[38:41], v[150:153], v[174:177], v[38:41]
	v_mfma_f32_16x16x32_bf16 v[38:41], v[146:149], v[170:173], v[38:41]
	v_mfma_f32_16x16x32_bf16 v[22:25], v[146:149], v[178:181], v[22:25]
	v_mfma_f32_16x16x32_bf16 v[22:25], v[150:153], v[182:185], v[22:25]
	v_mfma_f32_16x16x32_bf16 v[18:21], v[158:161], v[182:185], v[18:21]
	v_mfma_f32_16x16x32_bf16 v[18:21], v[154:157], v[178:181], v[18:21]
	v_mfma_f32_16x16x32_bf16 v[2:5], v[154:157], v[198:201], v[2:5]
	v_mfma_f32_16x16x32_bf16 v[2:5], v[158:161], v[202:205], v[2:5]
	v_mfma_f32_16x16x32_bf16 v[6:9], v[150:153], v[202:205], v[6:9]
	v_mfma_f32_16x16x32_bf16 v[6:9], v[146:149], v[198:201], v[6:9]
	s_barrier
; #define PG8_STAGE(bufoff, gbase, voff) do { _Pragma("unroll") for (int _i = 0; _i < 2; ++_i) \
;         __builtin_amdgcn_global_load_lds((const unsigned*)((const char*)(gbase) + (voff)[_i]), (PG8_LAS unsigned*)(lds + (bufoff) + ldsw + _i * 8192), 16, 0, 0); } while (0)
; #define PG8_LDA(dst, b, h) do { _Pragma("unroll") for (int m = 0; m < 4; ++m) _Pragma("unroll") for (int k = 0; k < 2; ++k) dst[m][k] = *(const PG8_LAS bf16x8*)(lds + PG8_SA(b, h) + aoff + m * 2048 + k * 1024); } while (0)
; #define PG8_LDB(dst, b, h) do { _Pragma("unroll") for (int n = 0; n < 2; ++n) _Pragma("unroll") for (int k = 0; k < 2; ++k) dst[n][k] = *(const PG8_LAS bf16x8*)(lds + PG8_SB(b, h) + boff + n * 2048 + k * 1024); } while (0)
; #define PG8_MMA(ai, bj, At, Bt) do { __builtin_amdgcn_s_setprio(1); _Pragma("unroll") for (int m = 0; m < 4; ++m) _Pragma("unroll") for (int n = 0; n < 2; ++n) _Pragma("unroll") for (int k = 0; k < 2; ++k) \
;         acc[ai][bj][m][n] = __builtin_amdgcn_mfma_f32_16x16x32_bf16(Bt[n][k], At[m][k], acc[ai][bj][m][n], 0, 0, 0); __builtin_amdgcn_s_setprio(0); } while (0)
; #define PG8_WAIT_V(n) asm volatile("s_waitcnt vmcnt(" #n ")" ::: "memory")
; #define PG8_WAIT_L(n) asm volatile("s_waitcnt lgkmcnt(" #n ")" ::: "memory")
; #define PG8_BAR __builtin_amdgcn_s_barrier()
; #define PG8_SCHED __builtin_amdgcn_sched_barrier(0)
;     ...
;         for (int t = 0; t < nt; t += 2) {
;             const bool last = (t == nt - 2);
;     ...
;             PG8_LDB(B0, 1, 0); PG8_LDB(B1, 1, 1); PG8_SCHED; PG8_LDA(At, 1, 0); PG8_STAGE(PG8_SA(0, 1), a2 + hstepA, voffA);
;             PG8_WAIT_V(8); PG8_WAIT_L(0); PG8_BAR; PG8_MMA(0, 0, At, B0); PG8_MMA(0, 1, At, B1); PG8_BAR; PG8_SCHED;
;             PG8_LDA(At, 1, 1); PG8_STAGE(PG8_SB(1, 0), b3, voffB); PG8_STAGE(PG8_SB(1, 1), b3 + hstepB, voffB); PG8_STAGE(PG8_SA(1, 0), a3, voffA);
;             PG8_WAIT_V(8); PG8_WAIT_L(0); PG8_BAR; PG8_MMA(1, 0, At, B0); PG8_MMA(1, 1, At, B1); PG8_BAR; PG8_SCHED;
	s_add_i32 s65, 0, 0x18000
	v_add_u32_e32 v0, s65, v242
	s_add_i32 s66, 0, 0x1c000
	ds_read_b128 v[130:133], v0
	ds_read_b128 v[134:137], v0 offset:1024
	ds_read_b128 v[138:141], v0 offset:2048
	ds_read_b128 v[142:145], v0 offset:3072
	v_add_u32_e32 v0, s66, v242
	ds_read_b128 v[146:149], v0
	ds_read_b128 v[150:153], v0 offset:1024
	ds_read_b128 v[154:157], v0 offset:2048
	ds_read_b128 v[158:161], v0 offset:3072
	s_add_u32 s86, s86, 0x4000
	s_addc_u32 s87, s87, 0
	s_mov_b32 m0, s55
	ds_read_b128 v[162:165], v243 offset:32768
	ds_read_b128 v[166:169], v243 offset:33792
	ds_read_b128 v[170:173], v243 offset:34816
	ds_read_b128 v[174:177], v243 offset:35840
	ds_read_b128 v[178:181], v243 offset:36864
	ds_read_b128 v[182:185], v243 offset:37888
	ds_read_b128 v[198:201], v243 offset:38912
	ds_read_b128 v[202:205], v243 offset:39936
	global_load_lds_dwordx4 v186, s[86:87]
	s_mov_b32 m0, s61
	s_nop 0
	global_load_lds_dwordx4 v190, s[86:87]
	s_waitcnt vmcnt(8)
	s_waitcnt lgkmcnt(0)
	s_barrier
	s_waitcnt lgkmcnt(0)
	v_mfma_f32_16x16x32_bf16 v[126:129], v[130:133], v[162:165], v[126:129]
	v_mfma_f32_16x16x32_bf16 v[126:129], v[134:137], v[166:169], v[126:129]
	v_mfma_f32_16x16x32_bf16 v[122:125], v[142:145], v[166:169], v[122:125]
	v_mfma_f32_16x16x32_bf16 v[122:125], v[138:141], v[162:165], v[122:125]
	v_mfma_f32_16x16x32_bf16 v[106:109], v[138:141], v[170:173], v[106:109]
	v_mfma_f32_16x16x32_bf16 v[106:109], v[142:145], v[174:177], v[106:109]
	v_mfma_f32_16x16x32_bf16 v[110:113], v[134:137], v[174:177], v[110:113]
	v_mfma_f32_16x16x32_bf16 v[110:113], v[130:133], v[170:173], v[110:113]
	v_mfma_f32_16x16x32_bf16 v[94:97], v[130:133], v[178:181], v[94:97]
	v_mfma_f32_16x16x32_bf16 v[94:97], v[134:137], v[182:185], v[94:97]
	v_mfma_f32_16x16x32_bf16 v[90:93], v[142:145], v[182:185], v[90:93]
	v_mfma_f32_16x16x32_bf16 v[90:93], v[138:141], v[178:181], v[90:93]
	v_mfma_f32_16x16x32_bf16 v[74:77], v[138:141], v[198:201], v[74:77]
	v_mfma_f32_16x16x32_bf16 v[74:77], v[142:145], v[202:205], v[74:77]
	v_mfma_f32_16x16x32_bf16 v[78:81], v[134:137], v[202:205], v[78:81]
	v_mfma_f32_16x16x32_bf16 v[78:81], v[130:133], v[198:201], v[78:81]
	v_mfma_f32_16x16x32_bf16 v[118:121], v[146:149], v[162:165], v[118:121]
	v_mfma_f32_16x16x32_bf16 v[118:121], v[150:153], v[166:169], v[118:121]
	v_mfma_f32_16x16x32_bf16 v[114:117], v[158:161], v[166:169], v[114:117]
	v_mfma_f32_16x16x32_bf16 v[114:117], v[154:157], v[162:165], v[114:117]
	v_mfma_f32_16x16x32_bf16 v[98:101], v[154:157], v[170:173], v[98:101]
	v_mfma_f32_16x16x32_bf16 v[98:101], v[158:161], v[174:177], v[98:101]
	v_mfma_f32_16x16x32_bf16 v[102:105], v[150:153], v[174:177], v[102:105]
	v_mfma_f32_16x16x32_bf16 v[102:105], v[146:149], v[170:173], v[102:105]
	v_mfma_f32_16x16x32_bf16 v[86:89], v[146:149], v[178:181], v[86:89]
	v_mfma_f32_16x16x32_bf16 v[86:89], v[150:153], v[182:185], v[86:89]
	v_mfma_f32_16x16x32_bf16 v[82:85], v[158:161], v[182:185], v[82:85]
	v_mfma_f32_16x16x32_bf16 v[82:85], v[154:157], v[178:181], v[82:85]
	v_mfma_f32_16x16x32_bf16 v[66:69], v[154:157], v[198:201], v[66:69]
	v_mfma_f32_16x16x32_bf16 v[66:69], v[158:161], v[202:205], v[66:69]
	v_mfma_f32_16x16x32_bf16 v[70:73], v[150:153], v[202:205], v[70:73]
	v_mfma_f32_16x16x32_bf16 v[70:73], v[146:149], v[198:201], v[70:73]
	s_barrier
	s_add_u32 s86, s46, 0x8000
	s_addc_u32 s87, s47, 0
	s_add_i32 s65, s65, s49
	s_mov_b32 m0, s65
	ds_read_b128 v[162:165], v243 offset:49152
	ds_read_b128 v[166:169], v243 offset:50176
	ds_read_b128 v[170:173], v243 offset:51200
	ds_read_b128 v[174:177], v243 offset:52224
	ds_read_b128 v[178:181], v243 offset:53248
	ds_read_b128 v[182:185], v243 offset:54272
	ds_read_b128 v[198:201], v243 offset:55296
	ds_read_b128 v[202:205], v243 offset:56320
	global_load_lds_dwordx4 v188, s[86:87]
	s_add_i32 m0, s65, 0x2000
	s_add_u32 s46, s46, 0xc000
	s_addc_u32 s47, s47, 0
	s_add_i32 s65, s66, s49
	global_load_lds_dwordx4 v192, s[86:87]
	s_mov_b32 m0, s65
	s_nop 0
	global_load_lds_dwordx4 v188, s[46:47]
	s_add_i32 m0, s65, 0x2000
	s_nop 0
	global_load_lds_dwordx4 v192, s[46:47]
	s_mov_b32 m0, s83
	s_nop 0
	global_load_lds_dwordx4 v186, s[36:37]
	v_lshl_add_u64 v[206:207], s[36:37], 0, v[190:191]
	s_mov_b32 m0, s85
	s_nop 0
	global_load_lds_dwordx4 v[206:207], off
	s_waitcnt vmcnt(8)
	s_waitcnt lgkmcnt(0)
	s_barrier
	s_waitcnt lgkmcnt(0)
	v_mfma_f32_16x16x32_bf16 v[62:65], v[130:133], v[162:165], v[62:65]
	v_mfma_f32_16x16x32_bf16 v[62:65], v[134:137], v[166:169], v[62:65]
	v_mfma_f32_16x16x32_bf16 v[58:61], v[142:145], v[166:169], v[58:61]
	v_mfma_f32_16x16x32_bf16 v[58:61], v[138:141], v[162:165], v[58:61]
	v_mfma_f32_16x16x32_bf16 v[42:45], v[138:141], v[170:173], v[42:45]
	v_mfma_f32_16x16x32_bf16 v[42:45], v[142:145], v[174:177], v[42:45]
	v_mfma_f32_16x16x32_bf16 v[46:49], v[134:137], v[174:177], v[46:49]
	v_mfma_f32_16x16x32_bf16 v[46:49], v[130:133], v[170:173], v[46:49]
	v_mfma_f32_16x16x32_bf16 v[30:33], v[130:133], v[178:181], v[30:33]
	v_mfma_f32_16x16x32_bf16 v[30:33], v[134:137], v[182:185], v[30:33]
	v_mfma_f32_16x16x32_bf16 v[26:29], v[142:145], v[182:185], v[26:29]
	v_mfma_f32_16x16x32_bf16 v[26:29], v[138:141], v[178:181], v[26:29]
	v_mfma_f32_16x16x32_bf16 v[10:13], v[138:141], v[198:201], v[10:13]
	v_mfma_f32_16x16x32_bf16 v[10:13], v[142:145], v[202:205], v[10:13]
	v_mfma_f32_16x16x32_bf16 v[14:17], v[134:137], v[202:205], v[14:17]
	v_mfma_f32_16x16x32_bf16 v[14:17], v[130:133], v[198:201], v[14:17]
	v_mfma_f32_16x16x32_bf16 v[54:57], v[146:149], v[162:165], v[54:57]
	v_mfma_f32_16x16x32_bf16 v[54:57], v[150:153], v[166:169], v[54:57]
	v_mfma_f32_16x16x32_bf16 v[50:53], v[158:161], v[166:169], v[50:53]
	v_mfma_f32_16x16x32_bf16 v[50:53], v[154:157], v[162:165], v[50:53]
	v_mfma_f32_16x16x32_bf16 v[34:37], v[154:157], v[170:173], v[34:37]
	v_mfma_f32_16x16x32_bf16 v[34:37], v[158:161], v[174:177], v[34:37]
	v_mfma_f32_16x16x32_bf16 v[38:41], v[150:153], v[174:177], v[38:41]
	v_mfma_f32_16x16x32_bf16 v[38:41], v[146:149], v[170:173], v[38:41]
	v_mfma_f32_16x16x32_bf16 v[22:25], v[146:149], v[178:181], v[22:25]
	v_mfma_f32_16x16x32_bf16 v[22:25], v[150:153], v[182:185], v[22:25]
	v_mfma_f32_16x16x32_bf16 v[18:21], v[158:161], v[182:185], v[18:21]
	v_mfma_f32_16x16x32_bf16 v[18:21], v[154:157], v[178:181], v[18:21]
	v_mfma_f32_16x16x32_bf16 v[2:5], v[154:157], v[198:201], v[2:5]
	v_mfma_f32_16x16x32_bf16 v[2:5], v[158:161], v[202:205], v[2:5]
	v_mfma_f32_16x16x32_bf16 v[6:9], v[150:153], v[202:205], v[6:9]
	v_mfma_f32_16x16x32_bf16 v[6:9], v[146:149], v[198:201], v[6:9]
	s_barrier
	s_add_i32 s57, s57, 2
	s_add_u32 s34, s34, 0x10000
	s_addc_u32 s35, s35, 0
	s_add_u32 s44, s44, 0x10000
	s_addc_u32 s56, s56, 0
	s_cmp_gt_u32 s57, 29
	s_cbranch_scc0 .LBB0_1128
	s_and_b64 vcc, exec, s[92:93]
	s_cbranch_vccz .LBB0_1131
	s_barrier

; #define PG8_STAGE(bufoff, gbase, voff) do { _Pragma("unroll") for (int _i = 0; _i < 2; ++_i) \
;         __builtin_amdgcn_global_load_lds((const unsigned*)((const char*)(gbase) + (voff)[_i]), (PG8_LAS unsigned*)(lds + (bufoff) + ldsw + _i * 8192), 16, 0, 0); } while (0)
; #define PG8_LDA(dst, b, h) do { _Pragma("unroll") for (int m = 0; m < 4; ++m) _Pragma("unroll") for (int k = 0; k < 2; ++k) dst[m][k] = *(const PG8_LAS bf16x8*)(lds + PG8_SA(b, h) + aoff + m * 2048 + k * 1024); } while (0)
; #define PG8_LDB(dst, b, h) do { _Pragma("unroll") for (int n = 0; n < 2; ++n) _Pragma("unroll") for (int k = 0; k < 2; ++k) dst[n][k] = *(const PG8_LAS bf16x8*)(lds + PG8_SB(b, h) + boff + n * 2048 + k * 1024); } while (0)
; #define PG8_MMA(ai, bj, At, Bt) do { __builtin_amdgcn_s_setprio(1); _Pragma("unroll") for (int m = 0; m < 4; ++m) _Pragma("unroll") for (int n = 0; n < 2; ++n) _Pragma("unroll") for (int k = 0; k < 2; ++k) \
;         acc[ai][bj][m][n] = __builtin_amdgcn_mfma_f32_16x16x32_bf16(Bt[n][k], At[m][k], acc[ai][bj][m][n], 0, 0, 0); __builtin_amdgcn_s_setprio(0); } while (0)
; #define PG8_WAIT_V(n) asm volatile("s_waitcnt vmcnt(" #n ")" ::: "memory")
; #define PG8_WAIT_L(n) asm volatile("s_waitcnt lgkmcnt(" #n ")" ::: "memory")
; #define PG8_BAR __builtin_amdgcn_s_barrier()
; #define PG8_SCHED __builtin_amdgcn_sched_barrier(0)
;     ...
;             const char* a1 = cA + (ptrdiff_t)(t + 1) * kstepA;
;             const char* a2 = last ? nA : cA + (ptrdiff_t)(t + 2) * kstepA; const char* b2 = last ? nB : cB + (ptrdiff_t)(t + 2) * kstep;
;             const char* a3 = a2 + kstepA; const char* b3 = b2 + kstep;
;             if (last && has_next) S.a_ready(nxt);
;             if constexpr (SP2) {
;             PG8_LDB(B0, 0, 0); PG8_LDB(B1, 0, 1); PG8_SCHED; PG8_LDA(At, 0, 0); PG8_STAGE(PG8_SA(1, 1), a1 + hstepA, voffA);
;             PG8_WAIT_V(8); PG8_WAIT_L(0); PG8_BAR; PG8_MMA(0, 0, At, B0); PG8_MMA(0, 1, At, B1); PG8_BAR; PG8_SCHED;
;             PG8_LDA(At, 0, 1); PG8_STAGE(PG8_SB(0, 0), b2, voffB); PG8_STAGE(PG8_SB(0, 1), b2 + hstepB, voffB); PG8_STAGE(PG8_SA(0, 0), a2, voffA);
;             PG8_WAIT_V(8); PG8_WAIT_L(0); PG8_BAR; PG8_MMA(1, 0, At, B0); PG8_MMA(1, 1, At, B1); PG8_BAR; PG8_SCHED;
.LBB0_1256:
	s_add_u32 s36, s34, 0x10000
	s_addc_u32 s37, s35, 0
	s_cmp_eq_u32 s66, 28
	s_cselect_b32 s88, s57, s36
	s_cselect_b32 s89, s27, s37
	s_cselect_b32 s86, vcc_lo, vcc_hi
	s_cselect_b32 s87, s25, s65
	s_add_u32 s46, s88, 0x8000
	s_addc_u32 s47, s89, 0
	s_add_i32 s96, 0, 0x10000
	v_add_u32_e32 v0, s96, v192
	s_add_i32 s97, 0, 0x14000
	ds_read_b128 v[130:133], v0
	ds_read_b128 v[134:137], v0 offset:1024
	ds_read_b128 v[138:141], v0 offset:2048
	ds_read_b128 v[142:145], v0 offset:3072
	v_add_u32_e32 v0, s97, v192
	ds_read_b128 v[146:149], v0
	ds_read_b128 v[150:153], v0 offset:1024
	ds_read_b128 v[154:157], v0 offset:2048
	ds_read_b128 v[170:173], v0 offset:3072
	s_add_i32 m0, s48, 0xc000
	ds_read_b128 v[174:177], v193
	ds_read_b128 v[178:181], v193 offset:1024
	ds_read_b128 v[182:185], v193 offset:2048
	ds_read_b128 v[186:189], v193 offset:3072
	ds_read_b128 v[194:197], v193 offset:4096
	ds_read_b128 v[198:201], v193 offset:5120
	ds_read_b128 v[202:205], v193 offset:6144
	ds_read_b128 v[206:209], v193 offset:7168
	global_load_lds_dwordx4 v166, s[34:35]
	s_add_i32 m0, s48, 0xe000
	s_nop 0
	global_load_lds_dwordx4 v168, s[34:35]
	s_waitcnt vmcnt(8)
	s_waitcnt lgkmcnt(0)
	s_barrier
	s_waitcnt lgkmcnt(0)
	v_mfma_f32_16x16x32_bf16 v[126:129], v[130:133], v[174:177], v[126:129]
	v_mfma_f32_16x16x32_bf16 v[126:129], v[134:137], v[178:181], v[126:129]
	v_mfma_f32_16x16x32_bf16 v[122:125], v[142:145], v[178:181], v[122:125]
	v_mfma_f32_16x16x32_bf16 v[122:125], v[138:141], v[174:177], v[122:125]
	v_mfma_f32_16x16x32_bf16 v[114:117], v[138:141], v[182:185], v[114:117]
	v_mfma_f32_16x16x32_bf16 v[114:117], v[142:145], v[186:189], v[114:117]
	v_mfma_f32_16x16x32_bf16 v[118:121], v[134:137], v[186:189], v[118:121]
	v_mfma_f32_16x16x32_bf16 v[118:121], v[130:133], v[182:185], v[118:121]
	v_mfma_f32_16x16x32_bf16 v[110:113], v[130:133], v[194:197], v[110:113]
	v_mfma_f32_16x16x32_bf16 v[110:113], v[134:137], v[198:201], v[110:113]
	v_mfma_f32_16x16x32_bf16 v[106:109], v[142:145], v[198:201], v[106:109]
	v_mfma_f32_16x16x32_bf16 v[106:109], v[138:141], v[194:197], v[106:109]
	v_mfma_f32_16x16x32_bf16 v[98:101], v[138:141], v[202:205], v[98:101]
	v_mfma_f32_16x16x32_bf16 v[98:101], v[142:145], v[206:209], v[98:101]
	v_mfma_f32_16x16x32_bf16 v[102:105], v[134:137], v[206:209], v[102:105]
	v_mfma_f32_16x16x32_bf16 v[102:105], v[130:133], v[202:205], v[102:105]
	v_mfma_f32_16x16x32_bf16 v[30:33], v[146:149], v[174:177], v[30:33]
	v_mfma_f32_16x16x32_bf16 v[30:33], v[150:153], v[178:181], v[30:33]
	v_mfma_f32_16x16x32_bf16 v[46:49], v[170:173], v[178:181], v[46:49]
	v_mfma_f32_16x16x32_bf16 v[46:49], v[154:157], v[174:177], v[46:49]
	v_mfma_f32_16x16x32_bf16 v[34:37], v[154:157], v[182:185], v[34:37]
	v_mfma_f32_16x16x32_bf16 v[34:37], v[170:173], v[186:189], v[34:37]
	v_mfma_f32_16x16x32_bf16 v[26:29], v[150:153], v[186:189], v[26:29]
	v_mfma_f32_16x16x32_bf16 v[26:29], v[146:149], v[182:185], v[26:29]
	v_mfma_f32_16x16x32_bf16 v[94:97], v[146:149], v[194:197], v[94:97]
	v_mfma_f32_16x16x32_bf16 v[94:97], v[150:153], v[198:201], v[94:97]
	v_mfma_f32_16x16x32_bf16 v[90:93], v[170:173], v[198:201], v[90:93]
	v_mfma_f32_16x16x32_bf16 v[90:93], v[154:157], v[194:197], v[90:93]
	v_mfma_f32_16x16x32_bf16 v[82:85], v[154:157], v[202:205], v[82:85]
	v_mfma_f32_16x16x32_bf16 v[82:85], v[170:173], v[206:209], v[82:85]
	v_mfma_f32_16x16x32_bf16 v[86:89], v[150:153], v[206:209], v[86:89]
	v_mfma_f32_16x16x32_bf16 v[86:89], v[146:149], v[202:205], v[86:89]
	s_barrier
	s_add_i32 s34, s96, s44
	s_mov_b32 m0, s34
	ds_read_b128 v[174:177], v193 offset:16384
	ds_read_b128 v[178:181], v193 offset:17408
	ds_read_b128 v[182:185], v193 offset:18432
	ds_read_b128 v[186:189], v193 offset:19456
	ds_read_b128 v[194:197], v193 offset:20480
	ds_read_b128 v[198:201], v193 offset:21504
	ds_read_b128 v[202:205], v193 offset:22528
	ds_read_b128 v[206:209], v193 offset:23552
	global_load_lds_dwordx4 v162, s[86:87]
	s_add_i32 m0, s34, 0x2000
	s_add_u32 s34, s86, 0x4000
	s_addc_u32 s35, s87, 0
	s_add_i32 s96, s97, s44
	global_load_lds_dwordx4 v158, s[86:87]
	s_mov_b32 m0, s96
	v_lshl_add_u64 v[210:211], s[88:89], 0, v[160:161]
	global_load_lds_dwordx4 v162, s[34:35]
	s_add_i32 m0, s96, 0x2000
	s_nop 0
	global_load_lds_dwordx4 v158, s[34:35]
	v_lshl_add_u64 v[190:191], s[88:89], 0, v[164:165]
	s_mov_b32 m0, s48
	s_nop 0
	global_load_lds_dwordx4 v[190:191], off
	s_mov_b32 m0, s49
	s_nop 0
	global_load_lds_dwordx4 v[210:211], off
	s_waitcnt vmcnt(8)
	s_waitcnt lgkmcnt(0)
	s_barrier
	s_waitcnt lgkmcnt(0)
	v_mfma_f32_16x16x32_bf16 v[78:81], v[130:133], v[174:177], v[78:81]
	v_mfma_f32_16x16x32_bf16 v[78:81], v[134:137], v[178:181], v[78:81]
	v_mfma_f32_16x16x32_bf16 v[74:77], v[142:145], v[178:181], v[74:77]
	v_mfma_f32_16x16x32_bf16 v[74:77], v[138:141], v[174:177], v[74:77]
	v_mfma_f32_16x16x32_bf16 v[66:69], v[138:141], v[182:185], v[66:69]
	v_mfma_f32_16x16x32_bf16 v[66:69], v[142:145], v[186:189], v[66:69]
	v_mfma_f32_16x16x32_bf16 v[70:73], v[134:137], v[186:189], v[70:73]
	v_mfma_f32_16x16x32_bf16 v[70:73], v[130:133], v[182:185], v[70:73]
	v_mfma_f32_16x16x32_bf16 v[42:45], v[130:133], v[194:197], v[42:45]
	v_mfma_f32_16x16x32_bf16 v[42:45], v[134:137], v[198:201], v[42:45]
	v_mfma_f32_16x16x32_bf16 v[6:9], v[142:145], v[198:201], v[6:9]
	v_mfma_f32_16x16x32_bf16 v[6:9], v[138:141], v[194:197], v[6:9]
	v_mfma_f32_16x16x32_bf16 v[2:5], v[138:141], v[202:205], v[2:5]
	v_mfma_f32_16x16x32_bf16 v[2:5], v[142:145], v[206:209], v[2:5]
	v_mfma_f32_16x16x32_bf16 v[38:41], v[134:137], v[206:209], v[38:41]
	v_mfma_f32_16x16x32_bf16 v[38:41], v[130:133], v[202:205], v[38:41]
	v_mfma_f32_16x16x32_bf16 v[62:65], v[146:149], v[174:177], v[62:65]
	v_mfma_f32_16x16x32_bf16 v[62:65], v[150:153], v[178:181], v[62:65]
	v_mfma_f32_16x16x32_bf16 v[58:61], v[170:173], v[178:181], v[58:61]
	v_mfma_f32_16x16x32_bf16 v[58:61], v[154:157], v[174:177], v[58:61]
	v_mfma_f32_16x16x32_bf16 v[50:53], v[154:157], v[182:185], v[50:53]
	v_mfma_f32_16x16x32_bf16 v[50:53], v[170:173], v[186:189], v[50:53]
	v_mfma_f32_16x16x32_bf16 v[54:57], v[150:153], v[186:189], v[54:57]
	v_mfma_f32_16x16x32_bf16 v[54:57], v[146:149], v[182:185], v[54:57]
	v_mfma_f32_16x16x32_bf16 v[22:25], v[146:149], v[194:197], v[22:25]
	v_mfma_f32_16x16x32_bf16 v[22:25], v[150:153], v[198:201], v[22:25]
	v_mfma_f32_16x16x32_bf16 v[18:21], v[170:173], v[198:201], v[18:21]
	v_mfma_f32_16x16x32_bf16 v[18:21], v[154:157], v[194:197], v[18:21]
	v_mfma_f32_16x16x32_bf16 v[10:13], v[154:157], v[202:205], v[10:13]
	v_mfma_f32_16x16x32_bf16 v[10:13], v[170:173], v[206:209], v[10:13]
	v_mfma_f32_16x16x32_bf16 v[14:17], v[150:153], v[206:209], v[14:17]
	v_mfma_f32_16x16x32_bf16 v[14:17], v[146:149], v[202:205], v[14:17]
	s_barrier
; #define PG8_STAGE(bufoff, gbase, voff) do { _Pragma("unroll") for (int _i = 0; _i < 2; ++_i) \
;         __builtin_amdgcn_global_load_lds((const unsigned*)((const char*)(gbase) + (voff)[_i]), (PG8_LAS unsigned*)(lds + (bufoff) + ldsw + _i * 8192), 16, 0, 0); } while (0)
; #define PG8_LDA(dst, b, h) do { _Pragma("unroll") for (int m = 0; m < 4; ++m) _Pragma("unroll") for (int k = 0; k < 2; ++k) dst[m][k] = *(const PG8_LAS bf16x8*)(lds + PG8_SA(b, h) + aoff + m * 2048 + k * 1024); } while (0)
; #define PG8_LDB(dst, b, h) do { _Pragma("unroll") for (int n = 0; n < 2; ++n) _Pragma("unroll") for (int k = 0; k < 2; ++k) dst[n][k] = *(const PG8_LAS bf16x8*)(lds + PG8_SB(b, h) + boff + n * 2048 + k * 1024); } while (0)
; #define PG8_MMA(ai, bj, At, Bt) do { __builtin_amdgcn_s_setprio(1); _Pragma("unroll") for (int m = 0; m < 4; ++m) _Pragma("unroll") for (int n = 0; n < 2; ++n) _Pragma("unroll") for (int k = 0; k < 2; ++k) \
;         acc[ai][bj][m][n] = __builtin_amdgcn_mfma_f32_16x16x32_bf16(Bt[n][k], At[m][k], acc[ai][bj][m][n], 0, 0, 0); __builtin_amdgcn_s_setprio(0); } while (0)
; #define PG8_WAIT_V(n) asm volatile("s_waitcnt vmcnt(" #n ")" ::: "memory")
; #define PG8_WAIT_L(n) asm volatile("s_waitcnt lgkmcnt(" #n ")" ::: "memory")
; #define PG8_BAR __builtin_amdgcn_s_barrier()
; #define PG8_SCHED __builtin_amdgcn_sched_barrier(0)
;     ...
;         for (int t = 0; t < nt; t += 2) {
;             const bool last = (t == nt - 2);
;     ...
;             PG8_LDB(B0, 1, 0); PG8_LDB(B1, 1, 1); PG8_SCHED; PG8_LDA(At, 1, 0); PG8_STAGE(PG8_SA(0, 1), a2 + hstepA, voffA);
;             PG8_WAIT_V(8); PG8_WAIT_L(0); PG8_BAR; PG8_MMA(0, 0, At, B0); PG8_MMA(0, 1, At, B1); PG8_BAR; PG8_SCHED;
;             PG8_LDA(At, 1, 1); PG8_STAGE(PG8_SB(1, 0), b3, voffB); PG8_STAGE(PG8_SB(1, 1), b3 + hstepB, voffB); PG8_STAGE(PG8_SA(1, 0), a3, voffA);
;             PG8_WAIT_V(8); PG8_WAIT_L(0); PG8_BAR; PG8_MMA(1, 0, At, B0); PG8_MMA(1, 1, At, B1); PG8_BAR; PG8_SCHED;
	s_add_i32 s88, 0, 0x18000
	v_add_u32_e32 v0, s88, v192
	s_add_i32 s89, 0, 0x1c000
	ds_read_b128 v[130:133], v0
	ds_read_b128 v[134:137], v0 offset:1024
	ds_read_b128 v[138:141], v0 offset:2048
	ds_read_b128 v[142:145], v0 offset:3072
	v_add_u32_e32 v0, s89, v192
	ds_read_b128 v[146:149], v0
	ds_read_b128 v[150:153], v0 offset:1024
	ds_read_b128 v[154:157], v0 offset:2048
	ds_read_b128 v[170:173], v0 offset:3072
	s_mov_b32 m0, s51
	v_lshl_add_u64 v[190:191], v[190:191], 0, s[58:59]
	ds_read_b128 v[174:177], v193 offset:32768
	ds_read_b128 v[178:181], v193 offset:33792
	ds_read_b128 v[182:185], v193 offset:34816
	ds_read_b128 v[186:189], v193 offset:35840
	ds_read_b128 v[194:197], v193 offset:36864
	ds_read_b128 v[198:201], v193 offset:37888
	ds_read_b128 v[202:205], v193 offset:38912
	ds_read_b128 v[206:209], v193 offset:39936
	global_load_lds_dwordx4 v[190:191], off
	v_lshl_add_u64 v[190:191], v[210:211], 0, s[58:59]
	s_mov_b32 m0, s54
	s_nop 0
	global_load_lds_dwordx4 v[190:191], off
	s_waitcnt vmcnt(8)
	s_waitcnt lgkmcnt(0)
	s_barrier
	s_waitcnt lgkmcnt(0)
	v_mfma_f32_16x16x32_bf16 v[126:129], v[130:133], v[174:177], v[126:129]
	v_mfma_f32_16x16x32_bf16 v[126:129], v[134:137], v[178:181], v[126:129]
	v_mfma_f32_16x16x32_bf16 v[122:125], v[142:145], v[178:181], v[122:125]
	v_mfma_f32_16x16x32_bf16 v[122:125], v[138:141], v[174:177], v[122:125]
	v_mfma_f32_16x16x32_bf16 v[114:117], v[138:141], v[182:185], v[114:117]
	v_mfma_f32_16x16x32_bf16 v[114:117], v[142:145], v[186:189], v[114:117]
	v_mfma_f32_16x16x32_bf16 v[118:121], v[134:137], v[186:189], v[118:121]
	v_mfma_f32_16x16x32_bf16 v[118:121], v[130:133], v[182:185], v[118:121]
	v_mfma_f32_16x16x32_bf16 v[110:113], v[130:133], v[194:197], v[110:113]
	v_mfma_f32_16x16x32_bf16 v[110:113], v[134:137], v[198:201], v[110:113]
	v_mfma_f32_16x16x32_bf16 v[106:109], v[142:145], v[198:201], v[106:109]
	v_mfma_f32_16x16x32_bf16 v[106:109], v[138:141], v[194:197], v[106:109]
	v_mfma_f32_16x16x32_bf16 v[98:101], v[138:141], v[202:205], v[98:101]
	v_mfma_f32_16x16x32_bf16 v[98:101], v[142:145], v[206:209], v[98:101]
	v_mfma_f32_16x16x32_bf16 v[102:105], v[134:137], v[206:209], v[102:105]
	v_mfma_f32_16x16x32_bf16 v[102:105], v[130:133], v[202:205], v[102:105]
	v_mfma_f32_16x16x32_bf16 v[30:33], v[146:149], v[174:177], v[30:33]
	v_mfma_f32_16x16x32_bf16 v[30:33], v[150:153], v[178:181], v[30:33]
	v_mfma_f32_16x16x32_bf16 v[46:49], v[170:173], v[178:181], v[46:49]
	v_mfma_f32_16x16x32_bf16 v[46:49], v[154:157], v[174:177], v[46:49]
	v_mfma_f32_16x16x32_bf16 v[34:37], v[154:157], v[182:185], v[34:37]
	v_mfma_f32_16x16x32_bf16 v[34:37], v[170:173], v[186:189], v[34:37]
	v_mfma_f32_16x16x32_bf16 v[26:29], v[150:153], v[186:189], v[26:29]
	v_mfma_f32_16x16x32_bf16 v[26:29], v[146:149], v[182:185], v[26:29]
	v_mfma_f32_16x16x32_bf16 v[94:97], v[146:149], v[194:197], v[94:97]
	v_mfma_f32_16x16x32_bf16 v[94:97], v[150:153], v[198:201], v[94:97]
	v_mfma_f32_16x16x32_bf16 v[90:93], v[170:173], v[198:201], v[90:93]
	v_mfma_f32_16x16x32_bf16 v[90:93], v[154:157], v[194:197], v[90:93]
	v_mfma_f32_16x16x32_bf16 v[82:85], v[154:157], v[202:205], v[82:85]
	v_mfma_f32_16x16x32_bf16 v[82:85], v[170:173], v[206:209], v[82:85]
	v_mfma_f32_16x16x32_bf16 v[86:89], v[150:153], v[206:209], v[86:89]
	v_mfma_f32_16x16x32_bf16 v[86:89], v[146:149], v[202:205], v[86:89]
	s_barrier
	s_add_u32 s34, s86, 0x8000
	s_addc_u32 s35, s87, 0
	s_add_i32 s88, s88, s44
	s_mov_b32 m0, s88
	ds_read_b128 v[174:177], v193 offset:49152
	ds_read_b128 v[178:181], v193 offset:50176
	ds_read_b128 v[182:185], v193 offset:51200
	ds_read_b128 v[186:189], v193 offset:52224
	ds_read_b128 v[194:197], v193 offset:53248
	ds_read_b128 v[198:201], v193 offset:54272
	ds_read_b128 v[202:205], v193 offset:55296
	ds_read_b128 v[206:209], v193 offset:56320
	global_load_lds_dwordx4 v162, s[34:35]
	s_add_i32 m0, s88, 0x2000
	v_lshl_add_u64 v[190:191], s[34:35], 0, v[158:159]
	s_add_u32 s34, s86, 0xc000
	s_addc_u32 s35, s87, 0
	s_add_i32 s86, s89, s44
	global_load_lds_dwordx4 v[190:191], off
	s_mov_b32 m0, s86
	s_nop 0
	global_load_lds_dwordx4 v162, s[34:35]
	s_add_i32 m0, s86, 0x2000
	s_nop 0
	global_load_lds_dwordx4 v158, s[34:35]
	s_mov_b32 m0, s85
	s_nop 0
	global_load_lds_dwordx4 v164, s[46:47]
	v_lshl_add_u64 v[190:191], s[46:47], 0, v[160:161]
	s_mov_b32 m0, s90
	s_nop 0
	global_load_lds_dwordx4 v[190:191], off
	s_waitcnt vmcnt(8)
	s_waitcnt lgkmcnt(0)
	s_barrier
	s_waitcnt lgkmcnt(0)
	v_mfma_f32_16x16x32_bf16 v[78:81], v[130:133], v[174:177], v[78:81]
	v_mfma_f32_16x16x32_bf16 v[78:81], v[134:137], v[178:181], v[78:81]
	v_mfma_f32_16x16x32_bf16 v[74:77], v[142:145], v[178:181], v[74:77]
	v_mfma_f32_16x16x32_bf16 v[74:77], v[138:141], v[174:177], v[74:77]
	v_mfma_f32_16x16x32_bf16 v[66:69], v[138:141], v[182:185], v[66:69]
	v_mfma_f32_16x16x32_bf16 v[66:69], v[142:145], v[186:189], v[66:69]
	v_mfma_f32_16x16x32_bf16 v[70:73], v[134:137], v[186:189], v[70:73]
	v_mfma_f32_16x16x32_bf16 v[70:73], v[130:133], v[182:185], v[70:73]
	v_mfma_f32_16x16x32_bf16 v[42:45], v[130:133], v[194:197], v[42:45]
	v_mfma_f32_16x16x32_bf16 v[42:45], v[134:137], v[198:201], v[42:45]
	v_mfma_f32_16x16x32_bf16 v[6:9], v[142:145], v[198:201], v[6:9]
	v_mfma_f32_16x16x32_bf16 v[6:9], v[138:141], v[194:197], v[6:9]
	v_mfma_f32_16x16x32_bf16 v[2:5], v[138:141], v[202:205], v[2:5]
	v_mfma_f32_16x16x32_bf16 v[2:5], v[142:145], v[206:209], v[2:5]
	v_mfma_f32_16x16x32_bf16 v[38:41], v[134:137], v[206:209], v[38:41]
	v_mfma_f32_16x16x32_bf16 v[38:41], v[130:133], v[202:205], v[38:41]
	v_mfma_f32_16x16x32_bf16 v[62:65], v[146:149], v[174:177], v[62:65]
	v_mfma_f32_16x16x32_bf16 v[62:65], v[150:153], v[178:181], v[62:65]
	v_mfma_f32_16x16x32_bf16 v[58:61], v[170:173], v[178:181], v[58:61]
	v_mfma_f32_16x16x32_bf16 v[58:61], v[154:157], v[174:177], v[58:61]
	v_mfma_f32_16x16x32_bf16 v[50:53], v[154:157], v[182:185], v[50:53]
	v_mfma_f32_16x16x32_bf16 v[50:53], v[170:173], v[186:189], v[50:53]
	v_mfma_f32_16x16x32_bf16 v[54:57], v[150:153], v[186:189], v[54:57]
	v_mfma_f32_16x16x32_bf16 v[54:57], v[146:149], v[182:185], v[54:57]
	v_mfma_f32_16x16x32_bf16 v[22:25], v[146:149], v[194:197], v[22:25]
	v_mfma_f32_16x16x32_bf16 v[22:25], v[150:153], v[198:201], v[22:25]
	v_mfma_f32_16x16x32_bf16 v[18:21], v[170:173], v[198:201], v[18:21]
	v_mfma_f32_16x16x32_bf16 v[18:21], v[154:157], v[194:197], v[18:21]
	v_mfma_f32_16x16x32_bf16 v[10:13], v[154:157], v[202:205], v[10:13]
	v_mfma_f32_16x16x32_bf16 v[10:13], v[170:173], v[206:209], v[10:13]
	v_mfma_f32_16x16x32_bf16 v[14:17], v[150:153], v[206:209], v[14:17]
	v_mfma_f32_16x16x32_bf16 v[14:17], v[146:149], v[202:205], v[14:17]
	s_barrier
	s_add_i32 s66, s66, 2
	s_add_u32 vcc_hi, vcc_hi, 0x10000
	s_addc_u32 s65, s65, 0
	s_cmp_gt_u32 s66, 29
	s_mov_b64 s[34:35], s[36:37]
	s_cbranch_scc0 .LBB0_1256
	s_and_b64 vcc, exec, s[18:19]
	s_cbranch_vccz .LBB0_1259
	s_barrier

; #define PG8_STAGE(bufoff, gbase, voff) do { _Pragma("unroll") for (int _i = 0; _i < 2; ++_i) \
;         __builtin_amdgcn_global_load_lds((const unsigned*)((const char*)(gbase) + (voff)[_i]), (PG8_LAS unsigned*)(lds + (bufoff) + ldsw + _i * 8192), 16, 0, 0); } while (0)
; #define PG8_LDA(dst, b, h) do { _Pragma("unroll") for (int m = 0; m < 4; ++m) _Pragma("unroll") for (int k = 0; k < 2; ++k) dst[m][k] = *(const PG8_LAS bf16x8*)(lds + PG8_SA(b, h) + aoff + m * 2048 + k * 1024); } while (0)
; #define PG8_LDB(dst, b, h) do { _Pragma("unroll") for (int n = 0; n < 2; ++n) _Pragma("unroll") for (int k = 0; k < 2; ++k) dst[n][k] = *(const PG8_LAS bf16x8*)(lds + PG8_SB(b, h) + boff + n * 2048 + k * 1024); } while (0)
; #define PG8_MMA(ai, bj, At, Bt) do { __builtin_amdgcn_s_setprio(1); _Pragma("unroll") for (int m = 0; m < 4; ++m) _Pragma("unroll") for (int n = 0; n < 2; ++n) _Pragma("unroll") for (int k = 0; k < 2; ++k) \
;         acc[ai][bj][m][n] = __builtin_amdgcn_mfma_f32_16x16x32_bf16(Bt[n][k], At[m][k], acc[ai][bj][m][n], 0, 0, 0); __builtin_amdgcn_s_setprio(0); } while (0)
; #define PG8_WAIT_V(n) asm volatile("s_waitcnt vmcnt(" #n ")" ::: "memory")
; #define PG8_WAIT_L(n) asm volatile("s_waitcnt lgkmcnt(" #n ")" ::: "memory")
; #define PG8_BAR __builtin_amdgcn_s_barrier()
; #define PG8_SCHED __builtin_amdgcn_sched_barrier(0)
;     ...
;             const char* a1 = cA + (ptrdiff_t)(t + 1) * kstepA;
;             const char* a2 = last ? nA : cA + (ptrdiff_t)(t + 2) * kstepA; const char* b2 = last ? nB : cB + (ptrdiff_t)(t + 2) * kstep;
;             const char* a3 = a2 + kstepA; const char* b3 = b2 + kstep;
;             if (last && has_next) S.a_ready(nxt);
;             if constexpr (SP2) {
;             PG8_LDB(B0, 0, 0); PG8_LDB(B1, 0, 1); PG8_SCHED; PG8_LDA(At, 0, 0); PG8_STAGE(PG8_SA(1, 1), a1 + hstepA, voffA);
;             PG8_WAIT_V(8); PG8_WAIT_L(0); PG8_BAR; PG8_MMA(0, 0, At, B0); PG8_MMA(0, 1, At, B1); PG8_BAR; PG8_SCHED;
;             PG8_LDA(At, 0, 1); PG8_STAGE(PG8_SB(0, 0), b2, voffB); PG8_STAGE(PG8_SB(0, 1), b2 + hstepB, voffB); PG8_STAGE(PG8_SA(0, 0), a2, voffA);
;             PG8_WAIT_V(8); PG8_WAIT_L(0); PG8_BAR; PG8_MMA(1, 0, At, B0); PG8_MMA(1, 1, At, B1); PG8_BAR; PG8_SCHED;
.LBB0_1444:
	s_or_b32 s44, s56, 1
	s_lshl_b64 s[34:35], s[44:45], 15
	s_sub_u32 s34, 0, s34
	s_subb_u32 s35, 0, s35
	s_add_u32 s44, s28, s34
	s_addc_u32 s65, s29, s35
	s_add_u32 s34, s30, 0xffff8000
	s_addc_u32 s35, s31, -1
	s_add_i32 s66, 0, 0x10000
	v_add_u32_e32 v0, s66, v230
	s_add_i32 s90, 0, 0x14000
	s_waitcnt lgkmcnt(0)
	ds_read_b128 v[130:133], v0
	ds_read_b128 v[134:137], v0 offset:1024
	ds_read_b128 v[138:141], v0 offset:2048
	ds_read_b128 v[142:145], v0 offset:3072
	v_add_u32_e32 v0, s90, v230
	ds_read_b128 v[146:149], v0
	ds_read_b128 v[150:153], v0 offset:1024
	ds_read_b128 v[154:157], v0 offset:2048
	ds_read_b128 v[158:161], v0 offset:3072
	s_add_u32 s88, s44, 0x4000
	s_addc_u32 s89, s65, 0
	s_add_i32 m0, s46, 0xc000
	ds_read_b128 v[162:165], v231
	ds_read_b128 v[166:169], v231 offset:1024
	ds_read_b128 v[170:173], v231 offset:2048
	ds_read_b128 v[174:177], v231 offset:3072
	ds_read_b128 v[178:181], v231 offset:4096
	ds_read_b128 v[182:185], v231 offset:5120
	ds_read_b128 v[186:189], v231 offset:6144
	ds_read_b128 v[190:193], v231 offset:7168
	global_load_lds_dwordx4 v194, s[88:89]
	s_add_i32 m0, s46, 0xe000
	s_nop 0
	global_load_lds_dwordx4 v198, s[88:89]
	s_waitcnt vmcnt(8)
	s_waitcnt lgkmcnt(0)
	s_barrier
	s_waitcnt lgkmcnt(0)
	v_mfma_f32_16x16x32_bf16 v[126:129], v[130:133], v[162:165], v[126:129]
	v_mfma_f32_16x16x32_bf16 v[126:129], v[134:137], v[166:169], v[126:129]
	v_mfma_f32_16x16x32_bf16 v[122:125], v[142:145], v[166:169], v[122:125]
	v_mfma_f32_16x16x32_bf16 v[122:125], v[138:141], v[162:165], v[122:125]
	v_mfma_f32_16x16x32_bf16 v[106:109], v[138:141], v[170:173], v[106:109]
	v_mfma_f32_16x16x32_bf16 v[106:109], v[142:145], v[174:177], v[106:109]
	v_mfma_f32_16x16x32_bf16 v[110:113], v[134:137], v[174:177], v[110:113]
	v_mfma_f32_16x16x32_bf16 v[110:113], v[130:133], v[170:173], v[110:113]
	v_mfma_f32_16x16x32_bf16 v[94:97], v[130:133], v[178:181], v[94:97]
	v_mfma_f32_16x16x32_bf16 v[94:97], v[134:137], v[182:185], v[94:97]
	v_mfma_f32_16x16x32_bf16 v[90:93], v[142:145], v[182:185], v[90:93]
	v_mfma_f32_16x16x32_bf16 v[90:93], v[138:141], v[178:181], v[90:93]
	v_mfma_f32_16x16x32_bf16 v[74:77], v[138:141], v[186:189], v[74:77]
	v_mfma_f32_16x16x32_bf16 v[74:77], v[142:145], v[190:193], v[74:77]
	v_mfma_f32_16x16x32_bf16 v[78:81], v[134:137], v[190:193], v[78:81]
	v_mfma_f32_16x16x32_bf16 v[78:81], v[130:133], v[186:189], v[78:81]
	v_mfma_f32_16x16x32_bf16 v[118:121], v[146:149], v[162:165], v[118:121]
	v_mfma_f32_16x16x32_bf16 v[118:121], v[150:153], v[166:169], v[118:121]
	v_mfma_f32_16x16x32_bf16 v[114:117], v[158:161], v[166:169], v[114:117]
	v_mfma_f32_16x16x32_bf16 v[114:117], v[154:157], v[162:165], v[114:117]
	v_mfma_f32_16x16x32_bf16 v[98:101], v[154:157], v[170:173], v[98:101]
	v_mfma_f32_16x16x32_bf16 v[98:101], v[158:161], v[174:177], v[98:101]
	v_mfma_f32_16x16x32_bf16 v[102:105], v[150:153], v[174:177], v[102:105]
	v_mfma_f32_16x16x32_bf16 v[102:105], v[146:149], v[170:173], v[102:105]
	v_mfma_f32_16x16x32_bf16 v[86:89], v[146:149], v[178:181], v[86:89]
	v_mfma_f32_16x16x32_bf16 v[86:89], v[150:153], v[182:185], v[86:89]
	v_mfma_f32_16x16x32_bf16 v[82:85], v[158:161], v[182:185], v[82:85]
	v_mfma_f32_16x16x32_bf16 v[82:85], v[154:157], v[178:181], v[82:85]
	v_mfma_f32_16x16x32_bf16 v[66:69], v[154:157], v[186:189], v[66:69]
	v_mfma_f32_16x16x32_bf16 v[66:69], v[158:161], v[190:193], v[66:69]
	v_mfma_f32_16x16x32_bf16 v[70:73], v[150:153], v[190:193], v[70:73]
	v_mfma_f32_16x16x32_bf16 v[70:73], v[146:149], v[186:189], v[70:73]
	s_barrier
	s_add_i32 s44, s66, s41
	s_mov_b32 m0, s44
	ds_read_b128 v[162:165], v231 offset:16384
	ds_read_b128 v[166:169], v231 offset:17408
	ds_read_b128 v[170:173], v231 offset:18432
	ds_read_b128 v[174:177], v231 offset:19456
	ds_read_b128 v[178:181], v231 offset:20480
	ds_read_b128 v[182:185], v231 offset:21504
	ds_read_b128 v[186:189], v231 offset:22528
	ds_read_b128 v[190:193], v231 offset:23552
	global_load_lds_dwordx4 v196, s[8:9]
	s_add_i32 m0, s44, 0x2000
	s_add_u32 s88, s8, 0x4000
	s_addc_u32 s89, s9, 0
	s_add_i32 s44, s90, s41
	global_load_lds_dwordx4 v200, s[8:9]
	s_mov_b32 m0, s44
	s_nop 0
	global_load_lds_dwordx4 v196, s[88:89]
	s_add_i32 m0, s44, 0x2000
	s_nop 0
	global_load_lds_dwordx4 v200, s[88:89]
	s_mov_b32 m0, s46
	s_nop 0
	global_load_lds_dwordx4 v194, s[30:31]
	s_mov_b32 m0, s47
	s_nop 0
	global_load_lds_dwordx4 v198, s[30:31]
	s_waitcnt vmcnt(8)
	s_waitcnt lgkmcnt(0)
	s_barrier
	s_waitcnt lgkmcnt(0)
	v_mfma_f32_16x16x32_bf16 v[62:65], v[130:133], v[162:165], v[62:65]
	v_mfma_f32_16x16x32_bf16 v[62:65], v[134:137], v[166:169], v[62:65]
	v_mfma_f32_16x16x32_bf16 v[58:61], v[142:145], v[166:169], v[58:61]
	v_mfma_f32_16x16x32_bf16 v[58:61], v[138:141], v[162:165], v[58:61]
	v_mfma_f32_16x16x32_bf16 v[42:45], v[138:141], v[170:173], v[42:45]
	v_mfma_f32_16x16x32_bf16 v[42:45], v[142:145], v[174:177], v[42:45]
	v_mfma_f32_16x16x32_bf16 v[46:49], v[134:137], v[174:177], v[46:49]
	v_mfma_f32_16x16x32_bf16 v[46:49], v[130:133], v[170:173], v[46:49]
	v_mfma_f32_16x16x32_bf16 v[30:33], v[130:133], v[178:181], v[30:33]
	v_mfma_f32_16x16x32_bf16 v[30:33], v[134:137], v[182:185], v[30:33]
	v_mfma_f32_16x16x32_bf16 v[26:29], v[142:145], v[182:185], v[26:29]
	v_mfma_f32_16x16x32_bf16 v[26:29], v[138:141], v[178:181], v[26:29]
	v_mfma_f32_16x16x32_bf16 v[10:13], v[138:141], v[186:189], v[10:13]
	v_mfma_f32_16x16x32_bf16 v[10:13], v[142:145], v[190:193], v[10:13]
	v_mfma_f32_16x16x32_bf16 v[14:17], v[134:137], v[190:193], v[14:17]
	v_mfma_f32_16x16x32_bf16 v[14:17], v[130:133], v[186:189], v[14:17]
	v_mfma_f32_16x16x32_bf16 v[54:57], v[146:149], v[162:165], v[54:57]
	v_mfma_f32_16x16x32_bf16 v[54:57], v[150:153], v[166:169], v[54:57]
	v_mfma_f32_16x16x32_bf16 v[50:53], v[158:161], v[166:169], v[50:53]
	v_mfma_f32_16x16x32_bf16 v[50:53], v[154:157], v[162:165], v[50:53]
	v_mfma_f32_16x16x32_bf16 v[34:37], v[154:157], v[170:173], v[34:37]
	v_mfma_f32_16x16x32_bf16 v[34:37], v[158:161], v[174:177], v[34:37]
	v_mfma_f32_16x16x32_bf16 v[38:41], v[150:153], v[174:177], v[38:41]
	v_mfma_f32_16x16x32_bf16 v[38:41], v[146:149], v[170:173], v[38:41]
	v_mfma_f32_16x16x32_bf16 v[22:25], v[146:149], v[178:181], v[22:25]
	v_mfma_f32_16x16x32_bf16 v[22:25], v[150:153], v[182:185], v[22:25]
	v_mfma_f32_16x16x32_bf16 v[18:21], v[158:161], v[182:185], v[18:21]
	v_mfma_f32_16x16x32_bf16 v[18:21], v[154:157], v[178:181], v[18:21]
	v_mfma_f32_16x16x32_bf16 v[2:5], v[154:157], v[186:189], v[2:5]
	v_mfma_f32_16x16x32_bf16 v[2:5], v[158:161], v[190:193], v[2:5]
	v_mfma_f32_16x16x32_bf16 v[6:9], v[150:153], v[190:193], v[6:9]
	v_mfma_f32_16x16x32_bf16 v[6:9], v[146:149], v[186:189], v[6:9]
	s_barrier
; #define PG8_STAGE(bufoff, gbase, voff) do { _Pragma("unroll") for (int _i = 0; _i < 2; ++_i) \
;         __builtin_amdgcn_global_load_lds((const unsigned*)((const char*)(gbase) + (voff)[_i]), (PG8_LAS unsigned*)(lds + (bufoff) + ldsw + _i * 8192), 16, 0, 0); } while (0)
; #define PG8_LDA(dst, b, h) do { _Pragma("unroll") for (int m = 0; m < 4; ++m) _Pragma("unroll") for (int k = 0; k < 2; ++k) dst[m][k] = *(const PG8_LAS bf16x8*)(lds + PG8_SA(b, h) + aoff + m * 2048 + k * 1024); } while (0)
; #define PG8_LDB(dst, b, h) do { _Pragma("unroll") for (int n = 0; n < 2; ++n) _Pragma("unroll") for (int k = 0; k < 2; ++k) dst[n][k] = *(const PG8_LAS bf16x8*)(lds + PG8_SB(b, h) + boff + n * 2048 + k * 1024); } while (0)
; #define PG8_MMA(ai, bj, At, Bt) do { __builtin_amdgcn_s_setprio(1); _Pragma("unroll") for (int m = 0; m < 4; ++m) _Pragma("unroll") for (int n = 0; n < 2; ++n) _Pragma("unroll") for (int k = 0; k < 2; ++k) \
;         acc[ai][bj][m][n] = __builtin_amdgcn_mfma_f32_16x16x32_bf16(Bt[n][k], At[m][k], acc[ai][bj][m][n], 0, 0, 0); __builtin_amdgcn_s_setprio(0); } while (0)
; #define PG8_WAIT_V(n) asm volatile("s_waitcnt vmcnt(" #n ")" ::: "memory")
; #define PG8_WAIT_L(n) asm volatile("s_waitcnt lgkmcnt(" #n ")" ::: "memory")
; #define PG8_BAR __builtin_amdgcn_s_barrier()
; #define PG8_SCHED __builtin_amdgcn_sched_barrier(0)
;     ...
;             PG8_LDB(B0, 0, 0); PG8_LDB(B1, 0, 1); PG8_SCHED; PG8_LDA(At, 0, 0); PG8_STAGE(PG8_SA(1, 1), a1 + hstepA, voffA);
;             PG8_WAIT_V(8); PG8_WAIT_L(0); PG8_BAR; PG8_MMA(0, 0, At, B0); PG8_MMA(0, 1, At, B1); PG8_BAR; PG8_SCHED;
;             PG8_LDA(At, 0, 1); PG8_STAGE(PG8_SB(0, 0), b2, voffB); PG8_STAGE(PG8_SB(0, 1), b2 + hstepB, voffB); PG8_STAGE(PG8_SA(0, 0), a2, voffA);
;             PG8_WAIT_V(8); PG8_WAIT_L(0); PG8_BAR; PG8_MMA(1, 0, At, B0); PG8_MMA(1, 1, At, B1); PG8_BAR; PG8_SCHED;
;             PG8_LDB(B0, 1, 0); PG8_LDB(B1, 1, 1); PG8_SCHED; PG8_LDA(At, 1, 0); PG8_STAGE(PG8_SA(0, 1), a2 + hstepA, voffA);
;             PG8_WAIT_V(8); PG8_WAIT_L(0); PG8_BAR; PG8_MMA(0, 0, At, B0); PG8_MMA(0, 1, At, B1); PG8_BAR; PG8_SCHED;
;             PG8_LDA(At, 1, 1); PG8_STAGE(PG8_SB(1, 0), b3, voffB); PG8_STAGE(PG8_SB(1, 1), b3 + hstepB, voffB); PG8_STAGE(PG8_SA(1, 0), a3, voffA);
;             PG8_WAIT_V(8); PG8_WAIT_L(0); PG8_BAR; PG8_MMA(1, 0, At, B0); PG8_MMA(1, 1, At, B1); PG8_BAR; PG8_SCHED;
	s_add_i32 s44, 0, 0x18000
	v_add_u32_e32 v0, s44, v230
	s_add_i32 s65, 0, 0x1c000
	ds_read_b128 v[130:133], v0
	ds_read_b128 v[134:137], v0 offset:1024
	ds_read_b128 v[138:141], v0 offset:2048
	ds_read_b128 v[142:145], v0 offset:3072
	v_add_u32_e32 v0, s65, v230
	ds_read_b128 v[146:149], v0
	ds_read_b128 v[150:153], v0 offset:1024
	ds_read_b128 v[154:157], v0 offset:2048
	ds_read_b128 v[158:161], v0 offset:3072
	s_add_u32 s30, s30, 0x4000
	s_addc_u32 s31, s31, 0
	s_mov_b32 m0, s48
	ds_read_b128 v[162:165], v231 offset:32768
	ds_read_b128 v[166:169], v231 offset:33792
	ds_read_b128 v[170:173], v231 offset:34816
	ds_read_b128 v[174:177], v231 offset:35840
	ds_read_b128 v[178:181], v231 offset:36864
	ds_read_b128 v[182:185], v231 offset:37888
	ds_read_b128 v[186:189], v231 offset:38912
	ds_read_b128 v[190:193], v231 offset:39936
	global_load_lds_dwordx4 v194, s[30:31]
	s_mov_b32 m0, s49
	s_nop 0
	global_load_lds_dwordx4 v198, s[30:31]
	s_waitcnt vmcnt(8)
	s_waitcnt lgkmcnt(0)
	s_barrier
	s_waitcnt lgkmcnt(0)
	v_mfma_f32_16x16x32_bf16 v[126:129], v[130:133], v[162:165], v[126:129]
	v_mfma_f32_16x16x32_bf16 v[126:129], v[134:137], v[166:169], v[126:129]
	v_mfma_f32_16x16x32_bf16 v[122:125], v[142:145], v[166:169], v[122:125]
	v_mfma_f32_16x16x32_bf16 v[122:125], v[138:141], v[162:165], v[122:125]
	v_mfma_f32_16x16x32_bf16 v[106:109], v[138:141], v[170:173], v[106:109]
	v_mfma_f32_16x16x32_bf16 v[106:109], v[142:145], v[174:177], v[106:109]
	v_mfma_f32_16x16x32_bf16 v[110:113], v[134:137], v[174:177], v[110:113]
	v_mfma_f32_16x16x32_bf16 v[110:113], v[130:133], v[170:173], v[110:113]
	v_mfma_f32_16x16x32_bf16 v[94:97], v[130:133], v[178:181], v[94:97]
	v_mfma_f32_16x16x32_bf16 v[94:97], v[134:137], v[182:185], v[94:97]
	v_mfma_f32_16x16x32_bf16 v[90:93], v[142:145], v[182:185], v[90:93]
	v_mfma_f32_16x16x32_bf16 v[90:93], v[138:141], v[178:181], v[90:93]
	v_mfma_f32_16x16x32_bf16 v[74:77], v[138:141], v[186:189], v[74:77]
	v_mfma_f32_16x16x32_bf16 v[74:77], v[142:145], v[190:193], v[74:77]
	v_mfma_f32_16x16x32_bf16 v[78:81], v[134:137], v[190:193], v[78:81]
	v_mfma_f32_16x16x32_bf16 v[78:81], v[130:133], v[186:189], v[78:81]
	v_mfma_f32_16x16x32_bf16 v[118:121], v[146:149], v[162:165], v[118:121]
	v_mfma_f32_16x16x32_bf16 v[118:121], v[150:153], v[166:169], v[118:121]
	v_mfma_f32_16x16x32_bf16 v[114:117], v[158:161], v[166:169], v[114:117]
	v_mfma_f32_16x16x32_bf16 v[114:117], v[154:157], v[162:165], v[114:117]
	v_mfma_f32_16x16x32_bf16 v[98:101], v[154:157], v[170:173], v[98:101]
	v_mfma_f32_16x16x32_bf16 v[98:101], v[158:161], v[174:177], v[98:101]
	v_mfma_f32_16x16x32_bf16 v[102:105], v[150:153], v[174:177], v[102:105]
	v_mfma_f32_16x16x32_bf16 v[102:105], v[146:149], v[170:173], v[102:105]
	v_mfma_f32_16x16x32_bf16 v[86:89], v[146:149], v[178:181], v[86:89]
	v_mfma_f32_16x16x32_bf16 v[86:89], v[150:153], v[182:185], v[86:89]
	v_mfma_f32_16x16x32_bf16 v[82:85], v[158:161], v[182:185], v[82:85]
	v_mfma_f32_16x16x32_bf16 v[82:85], v[154:157], v[178:181], v[82:85]
	v_mfma_f32_16x16x32_bf16 v[66:69], v[154:157], v[186:189], v[66:69]
	v_mfma_f32_16x16x32_bf16 v[66:69], v[158:161], v[190:193], v[66:69]
	v_mfma_f32_16x16x32_bf16 v[70:73], v[150:153], v[190:193], v[70:73]
	v_mfma_f32_16x16x32_bf16 v[70:73], v[146:149], v[186:189], v[70:73]
	s_barrier
	s_add_u32 s30, s8, 0xffff8000
	s_addc_u32 s31, s9, -1
	s_add_i32 s44, s44, s41
	s_mov_b32 m0, s44
	ds_read_b128 v[162:165], v231 offset:49152
	ds_read_b128 v[166:169], v231 offset:50176
	ds_read_b128 v[170:173], v231 offset:51200
	ds_read_b128 v[174:177], v231 offset:52224
	ds_read_b128 v[178:181], v231 offset:53248
	ds_read_b128 v[182:185], v231 offset:54272
	ds_read_b128 v[186:189], v231 offset:55296
	ds_read_b128 v[190:193], v231 offset:56320
	global_load_lds_dwordx4 v196, s[30:31]
	s_add_i32 m0, s44, 0x2000
	s_add_u32 s8, s8, 0xffffc000
	v_lshl_add_u64 v[202:203], s[30:31], 0, v[200:201]
	s_addc_u32 s9, s9, -1
	s_add_i32 s30, s65, s41
	global_load_lds_dwordx4 v[202:203], off
	s_mov_b32 m0, s30
	s_nop 0
	global_load_lds_dwordx4 v196, s[8:9]
	s_add_i32 m0, s30, 0x2000
	s_nop 0
	global_load_lds_dwordx4 v200, s[8:9]
	s_mov_b32 m0, s71
	s_nop 0
	global_load_lds_dwordx4 v194, s[34:35]
	v_lshl_add_u64 v[202:203], s[34:35], 0, v[198:199]
	s_mov_b32 m0, s80
	s_nop 0
	global_load_lds_dwordx4 v[202:203], off
	s_waitcnt vmcnt(8)
	s_waitcnt lgkmcnt(0)
	s_barrier
	s_waitcnt lgkmcnt(0)
	v_mfma_f32_16x16x32_bf16 v[62:65], v[130:133], v[162:165], v[62:65]
	v_mfma_f32_16x16x32_bf16 v[62:65], v[134:137], v[166:169], v[62:65]
	v_mfma_f32_16x16x32_bf16 v[58:61], v[142:145], v[166:169], v[58:61]
	v_mfma_f32_16x16x32_bf16 v[58:61], v[138:141], v[162:165], v[58:61]
	v_mfma_f32_16x16x32_bf16 v[42:45], v[138:141], v[170:173], v[42:45]
	v_mfma_f32_16x16x32_bf16 v[42:45], v[142:145], v[174:177], v[42:45]
	v_mfma_f32_16x16x32_bf16 v[46:49], v[134:137], v[174:177], v[46:49]
	v_mfma_f32_16x16x32_bf16 v[46:49], v[130:133], v[170:173], v[46:49]
	v_mfma_f32_16x16x32_bf16 v[30:33], v[130:133], v[178:181], v[30:33]
	v_mfma_f32_16x16x32_bf16 v[30:33], v[134:137], v[182:185], v[30:33]
	v_mfma_f32_16x16x32_bf16 v[26:29], v[142:145], v[182:185], v[26:29]
	v_mfma_f32_16x16x32_bf16 v[26:29], v[138:141], v[178:181], v[26:29]
	v_mfma_f32_16x16x32_bf16 v[10:13], v[138:141], v[186:189], v[10:13]
	v_mfma_f32_16x16x32_bf16 v[10:13], v[142:145], v[190:193], v[10:13]
	v_mfma_f32_16x16x32_bf16 v[14:17], v[134:137], v[190:193], v[14:17]
	v_mfma_f32_16x16x32_bf16 v[14:17], v[130:133], v[186:189], v[14:17]
	v_mfma_f32_16x16x32_bf16 v[54:57], v[146:149], v[162:165], v[54:57]
	v_mfma_f32_16x16x32_bf16 v[54:57], v[150:153], v[166:169], v[54:57]
	v_mfma_f32_16x16x32_bf16 v[50:53], v[158:161], v[166:169], v[50:53]
	v_mfma_f32_16x16x32_bf16 v[50:53], v[154:157], v[162:165], v[50:53]
	v_mfma_f32_16x16x32_bf16 v[34:37], v[154:157], v[170:173], v[34:37]
	v_mfma_f32_16x16x32_bf16 v[34:37], v[158:161], v[174:177], v[34:37]
	v_mfma_f32_16x16x32_bf16 v[38:41], v[150:153], v[174:177], v[38:41]
	v_mfma_f32_16x16x32_bf16 v[38:41], v[146:149], v[170:173], v[38:41]
	v_mfma_f32_16x16x32_bf16 v[22:25], v[146:149], v[178:181], v[22:25]
	v_mfma_f32_16x16x32_bf16 v[22:25], v[150:153], v[182:185], v[22:25]
	v_mfma_f32_16x16x32_bf16 v[18:21], v[158:161], v[182:185], v[18:21]
	v_mfma_f32_16x16x32_bf16 v[18:21], v[154:157], v[178:181], v[18:21]
	v_mfma_f32_16x16x32_bf16 v[2:5], v[154:157], v[186:189], v[2:5]
	v_mfma_f32_16x16x32_bf16 v[2:5], v[158:161], v[190:193], v[2:5]
	v_mfma_f32_16x16x32_bf16 v[6:9], v[150:153], v[190:193], v[6:9]
	v_mfma_f32_16x16x32_bf16 v[6:9], v[146:149], v[186:189], v[6:9]
	s_barrier
	s_cmpk_gt_u32 s56, 0x55
	s_mov_b32 s56, s57
	s_cbranch_scc1 .LBB0_1449
